# on top of the P0 rewrite: removed the s_setprio 0/1 flip in the middle of each 32-MFMA segment of the six GEMM K-loops (one priority raise per segment)
# speedup vs baseline: 1.0028x; 1.0028x over previous
.LBB0_237:
	ds_read_b128 v[150:153], v147
	ds_read_b128 v[154:157], v147 offset:1024
	ds_read_b128 v[158:161], v147 offset:2048
	ds_read_b128 v[162:165], v147 offset:3072
	ds_read_b128 v[166:169], v148
	ds_read_b128 v[170:173], v148 offset:1024
	ds_read_b128 v[174:177], v148 offset:2048
	ds_read_b128 v[178:181], v148 offset:3072
	s_add_u32 s22, s20, 0xfffc0080
	s_addc_u32 s23, s21, -1
	s_cmp_eq_u32 s48, 12
	s_cselect_b32 s25, s13, s23
	s_cselect_b32 s24, s44, s22
	s_cselect_b32 s23, s11, s47
	s_cselect_b32 s22, s45, s46
	v_lshl_add_u64 v[206:207], s[20:21], 0, v[136:137]
	s_add_i32 m0, s19, 0xc000
	ds_read_b128 v[182:185], v149
	ds_read_b128 v[186:189], v149 offset:1024
	ds_read_b128 v[190:193], v149 offset:2048
	ds_read_b128 v[194:197], v149 offset:3072
	ds_read_b128 v[198:201], v149 offset:4096
	ds_read_b128 v[202:205], v149 offset:5120
	ds_read_b128 v[210:213], v149 offset:6144
	ds_read_b128 v[214:217], v149 offset:7168
	global_load_lds_dwordx4 v[206:207], off
	v_lshl_add_u64 v[206:207], s[20:21], 0, v[138:139]
	s_add_i32 m0, s19, 0xe000
	s_nop 0
	global_load_lds_dwordx4 v[206:207], off
	s_waitcnt vmcnt(8)
	s_waitcnt lgkmcnt(0)
	s_barrier
	s_setprio 1
	s_waitcnt lgkmcnt(0)
	v_mfma_f32_16x16x32_bf16 v[124:127], v[150:153], v[182:185], v[124:127]
	v_mfma_f32_16x16x32_bf16 v[120:123], v[158:161], v[182:185], v[120:123]
	v_mfma_f32_16x16x32_bf16 v[108:111], v[150:153], v[190:193], v[108:111]
	v_mfma_f32_16x16x32_bf16 v[104:107], v[158:161], v[190:193], v[104:107]
	v_mfma_f32_16x16x32_bf16 v[92:95], v[150:153], v[198:201], v[92:95]
	v_mfma_f32_16x16x32_bf16 v[88:91], v[158:161], v[198:201], v[88:91]
	v_mfma_f32_16x16x32_bf16 v[76:79], v[150:153], v[210:213], v[76:79]
	v_mfma_f32_16x16x32_bf16 v[72:75], v[158:161], v[210:213], v[72:75]
	v_mfma_f32_16x16x32_bf16 v[124:127], v[154:157], v[186:189], v[124:127]
	v_mfma_f32_16x16x32_bf16 v[120:123], v[162:165], v[186:189], v[120:123]
	v_mfma_f32_16x16x32_bf16 v[108:111], v[154:157], v[194:197], v[108:111]
	v_mfma_f32_16x16x32_bf16 v[104:107], v[162:165], v[194:197], v[104:107]
	v_mfma_f32_16x16x32_bf16 v[92:95], v[154:157], v[202:205], v[92:95]
	v_mfma_f32_16x16x32_bf16 v[88:91], v[162:165], v[202:205], v[88:91]
	v_mfma_f32_16x16x32_bf16 v[76:79], v[154:157], v[214:217], v[76:79]
	v_mfma_f32_16x16x32_bf16 v[72:75], v[162:165], v[214:217], v[72:75]
	v_mfma_f32_16x16x32_bf16 v[116:119], v[166:169], v[182:185], v[116:119]
	v_mfma_f32_16x16x32_bf16 v[112:115], v[174:177], v[182:185], v[112:115]
	v_mfma_f32_16x16x32_bf16 v[100:103], v[166:169], v[190:193], v[100:103]
	v_mfma_f32_16x16x32_bf16 v[96:99], v[174:177], v[190:193], v[96:99]
	v_mfma_f32_16x16x32_bf16 v[84:87], v[166:169], v[198:201], v[84:87]
	v_mfma_f32_16x16x32_bf16 v[80:83], v[174:177], v[198:201], v[80:83]
	v_mfma_f32_16x16x32_bf16 v[68:71], v[166:169], v[210:213], v[68:71]
	v_mfma_f32_16x16x32_bf16 v[64:67], v[174:177], v[210:213], v[64:67]
	v_mfma_f32_16x16x32_bf16 v[116:119], v[170:173], v[186:189], v[116:119]
	v_mfma_f32_16x16x32_bf16 v[112:115], v[178:181], v[186:189], v[112:115]
	v_mfma_f32_16x16x32_bf16 v[100:103], v[170:173], v[194:197], v[100:103]
	v_mfma_f32_16x16x32_bf16 v[96:99], v[178:181], v[194:197], v[96:99]
	v_mfma_f32_16x16x32_bf16 v[84:87], v[170:173], v[202:205], v[84:87]
	v_mfma_f32_16x16x32_bf16 v[80:83], v[178:181], v[202:205], v[80:83]
	v_mfma_f32_16x16x32_bf16 v[68:71], v[170:173], v[214:217], v[68:71]
	v_mfma_f32_16x16x32_bf16 v[64:67], v[178:181], v[214:217], v[64:67]
	s_setprio 0
	s_barrier
	s_add_i32 s49, s40, s28
	v_lshl_add_u64 v[206:207], s[22:23], 0, v[132:133]
	s_mov_b32 m0, s49
	ds_read_b128 v[182:185], v149 offset:16384
	ds_read_b128 v[186:189], v149 offset:17408
	ds_read_b128 v[190:193], v149 offset:18432
	ds_read_b128 v[194:197], v149 offset:19456
	ds_read_b128 v[198:201], v149 offset:20480
	ds_read_b128 v[202:205], v149 offset:21504
	ds_read_b128 v[210:213], v149 offset:22528
	ds_read_b128 v[214:217], v149 offset:23552
	global_load_lds_dwordx4 v[206:207], off
	s_add_i32 m0, s49, 0x2000
	s_add_u32 s50, s22, 0x40000
	v_lshl_add_u64 v[218:219], s[22:23], 0, v[128:129]
	s_addc_u32 s51, s23, 0
	s_add_i32 s49, s41, s28
	global_load_lds_dwordx4 v[218:219], off
	v_lshl_add_u64 v[220:221], s[50:51], 0, v[132:133]
	s_mov_b32 m0, s49
	v_lshl_add_u64 v[222:223], s[24:25], 0, v[130:131]
	global_load_lds_dwordx4 v[220:221], off
	v_lshl_add_u64 v[220:221], s[50:51], 0, v[128:129]
	s_add_i32 m0, s49, 0x2000
	s_nop 0
	global_load_lds_dwordx4 v[220:221], off
	v_lshl_add_u64 v[220:221], s[24:25], 0, v[134:135]
	s_mov_b32 m0, s19
	s_nop 0
	global_load_lds_dwordx4 v[220:221], off
	s_mov_b32 m0, s31
	s_nop 0
	global_load_lds_dwordx4 v[222:223], off
	s_waitcnt vmcnt(8)
	s_waitcnt lgkmcnt(0)
	s_barrier
	s_setprio 1
	s_waitcnt lgkmcnt(0)
	v_mfma_f32_16x16x32_bf16 v[60:63], v[150:153], v[182:185], v[60:63]
	v_mfma_f32_16x16x32_bf16 v[56:59], v[158:161], v[182:185], v[56:59]
	v_mfma_f32_16x16x32_bf16 v[44:47], v[150:153], v[190:193], v[44:47]
	v_mfma_f32_16x16x32_bf16 v[40:43], v[158:161], v[190:193], v[40:43]
	v_mfma_f32_16x16x32_bf16 v[28:31], v[150:153], v[198:201], v[28:31]
	v_mfma_f32_16x16x32_bf16 v[24:27], v[158:161], v[198:201], v[24:27]
	v_mfma_f32_16x16x32_bf16 v[12:15], v[150:153], v[210:213], v[12:15]
	v_mfma_f32_16x16x32_bf16 v[8:11], v[158:161], v[210:213], v[8:11]
	v_mfma_f32_16x16x32_bf16 v[60:63], v[154:157], v[186:189], v[60:63]
	v_mfma_f32_16x16x32_bf16 v[56:59], v[162:165], v[186:189], v[56:59]
	v_mfma_f32_16x16x32_bf16 v[44:47], v[154:157], v[194:197], v[44:47]
	v_mfma_f32_16x16x32_bf16 v[40:43], v[162:165], v[194:197], v[40:43]
	v_mfma_f32_16x16x32_bf16 v[28:31], v[154:157], v[202:205], v[28:31]
	v_mfma_f32_16x16x32_bf16 v[24:27], v[162:165], v[202:205], v[24:27]
	v_mfma_f32_16x16x32_bf16 v[12:15], v[154:157], v[214:217], v[12:15]
	v_mfma_f32_16x16x32_bf16 v[8:11], v[162:165], v[214:217], v[8:11]
	v_mfma_f32_16x16x32_bf16 v[52:55], v[166:169], v[182:185], v[52:55]
	v_mfma_f32_16x16x32_bf16 v[48:51], v[174:177], v[182:185], v[48:51]
	v_mfma_f32_16x16x32_bf16 v[36:39], v[166:169], v[190:193], v[36:39]
	v_mfma_f32_16x16x32_bf16 v[32:35], v[174:177], v[190:193], v[32:35]
	v_mfma_f32_16x16x32_bf16 v[20:23], v[166:169], v[198:201], v[20:23]
	v_mfma_f32_16x16x32_bf16 v[16:19], v[174:177], v[198:201], v[16:19]
	v_mfma_f32_16x16x32_bf16 v[4:7], v[166:169], v[210:213], v[4:7]
	v_mfma_f32_16x16x32_bf16 v[0:3], v[174:177], v[210:213], v[0:3]
	v_mfma_f32_16x16x32_bf16 v[52:55], v[170:173], v[186:189], v[52:55]
	v_mfma_f32_16x16x32_bf16 v[48:51], v[178:181], v[186:189], v[48:51]
	v_mfma_f32_16x16x32_bf16 v[36:39], v[170:173], v[194:197], v[36:39]
	v_mfma_f32_16x16x32_bf16 v[32:35], v[178:181], v[194:197], v[32:35]
	v_mfma_f32_16x16x32_bf16 v[20:23], v[170:173], v[202:205], v[20:23]
	v_mfma_f32_16x16x32_bf16 v[16:19], v[178:181], v[202:205], v[16:19]
	v_mfma_f32_16x16x32_bf16 v[4:7], v[170:173], v[214:217], v[4:7]
	v_mfma_f32_16x16x32_bf16 v[0:3], v[178:181], v[214:217], v[0:3]
	s_setprio 0
	s_barrier
	s_add_i32 s49, 0, 0x18000
	s_add_i32 s50, 0, 0x1c000
	v_add_u32_e32 v162, s49, v145
	v_add_u32_e32 v178, s50, v145
	ds_read_b128 v[150:153], v162
	ds_read_b128 v[154:157], v162 offset:1024
	ds_read_b128 v[158:161], v162 offset:2048
	ds_read_b128 v[162:165], v162 offset:3072
	ds_read_b128 v[166:169], v178
	ds_read_b128 v[170:173], v178 offset:1024
	ds_read_b128 v[174:177], v178 offset:2048
	ds_read_b128 v[178:181], v178 offset:3072
	s_add_u32 s24, s24, 0x40000
	s_addc_u32 s25, s25, 0
	s_mov_b32 m0, s33
	v_lshl_add_u64 v[224:225], s[24:25], 0, v[134:135]
	ds_read_b128 v[182:185], v149 offset:32768
	ds_read_b128 v[186:189], v149 offset:33792
	ds_read_b128 v[190:193], v149 offset:34816
	ds_read_b128 v[194:197], v149 offset:35840
	ds_read_b128 v[198:201], v149 offset:36864
	ds_read_b128 v[202:205], v149 offset:37888
	ds_read_b128 v[210:213], v149 offset:38912
	ds_read_b128 v[214:217], v149 offset:39936
	global_load_lds_dwordx4 v[224:225], off
	v_lshl_add_u64 v[224:225], s[24:25], 0, v[130:131]
	s_mov_b32 m0, s34
	s_nop 0
	global_load_lds_dwordx4 v[224:225], off
	s_waitcnt vmcnt(8)
	s_waitcnt lgkmcnt(0)
	s_barrier
	s_setprio 1
	s_waitcnt lgkmcnt(0)
	v_mfma_f32_16x16x32_bf16 v[124:127], v[150:153], v[182:185], v[124:127]
	v_mfma_f32_16x16x32_bf16 v[120:123], v[158:161], v[182:185], v[120:123]
	v_mfma_f32_16x16x32_bf16 v[108:111], v[150:153], v[190:193], v[108:111]
	v_mfma_f32_16x16x32_bf16 v[104:107], v[158:161], v[190:193], v[104:107]
	v_mfma_f32_16x16x32_bf16 v[92:95], v[150:153], v[198:201], v[92:95]
	v_mfma_f32_16x16x32_bf16 v[88:91], v[158:161], v[198:201], v[88:91]
	v_mfma_f32_16x16x32_bf16 v[76:79], v[150:153], v[210:213], v[76:79]
	v_mfma_f32_16x16x32_bf16 v[72:75], v[158:161], v[210:213], v[72:75]
	v_mfma_f32_16x16x32_bf16 v[124:127], v[154:157], v[186:189], v[124:127]
	v_mfma_f32_16x16x32_bf16 v[120:123], v[162:165], v[186:189], v[120:123]
	v_mfma_f32_16x16x32_bf16 v[108:111], v[154:157], v[194:197], v[108:111]
	v_mfma_f32_16x16x32_bf16 v[104:107], v[162:165], v[194:197], v[104:107]
	v_mfma_f32_16x16x32_bf16 v[92:95], v[154:157], v[202:205], v[92:95]
	v_mfma_f32_16x16x32_bf16 v[88:91], v[162:165], v[202:205], v[88:91]
	v_mfma_f32_16x16x32_bf16 v[76:79], v[154:157], v[214:217], v[76:79]
	v_mfma_f32_16x16x32_bf16 v[72:75], v[162:165], v[214:217], v[72:75]
	v_mfma_f32_16x16x32_bf16 v[116:119], v[166:169], v[182:185], v[116:119]
	v_mfma_f32_16x16x32_bf16 v[112:115], v[174:177], v[182:185], v[112:115]
	v_mfma_f32_16x16x32_bf16 v[100:103], v[166:169], v[190:193], v[100:103]
	v_mfma_f32_16x16x32_bf16 v[96:99], v[174:177], v[190:193], v[96:99]
	v_mfma_f32_16x16x32_bf16 v[84:87], v[166:169], v[198:201], v[84:87]
	v_mfma_f32_16x16x32_bf16 v[80:83], v[174:177], v[198:201], v[80:83]
	v_mfma_f32_16x16x32_bf16 v[68:71], v[166:169], v[210:213], v[68:71]
	v_mfma_f32_16x16x32_bf16 v[64:67], v[174:177], v[210:213], v[64:67]
	v_mfma_f32_16x16x32_bf16 v[116:119], v[170:173], v[186:189], v[116:119]
	v_mfma_f32_16x16x32_bf16 v[112:115], v[178:181], v[186:189], v[112:115]
	v_mfma_f32_16x16x32_bf16 v[100:103], v[170:173], v[194:197], v[100:103]
	v_mfma_f32_16x16x32_bf16 v[96:99], v[178:181], v[194:197], v[96:99]
	v_mfma_f32_16x16x32_bf16 v[84:87], v[170:173], v[202:205], v[84:87]
	v_mfma_f32_16x16x32_bf16 v[80:83], v[178:181], v[202:205], v[80:83]
	v_mfma_f32_16x16x32_bf16 v[68:71], v[170:173], v[214:217], v[68:71]
	v_mfma_f32_16x16x32_bf16 v[64:67], v[178:181], v[214:217], v[64:67]
	s_setprio 0
	s_barrier
	s_add_i32 s24, s49, s28
	v_lshl_add_u64 v[206:207], v[206:207], 0, s[6:7]
	s_mov_b32 m0, s24
	ds_read_b128 v[182:185], v149 offset:49152
	ds_read_b128 v[186:189], v149 offset:50176
	ds_read_b128 v[190:193], v149 offset:51200
	ds_read_b128 v[194:197], v149 offset:52224
	ds_read_b128 v[198:201], v149 offset:53248
	ds_read_b128 v[202:205], v149 offset:54272
	ds_read_b128 v[210:213], v149 offset:55296
	ds_read_b128 v[214:217], v149 offset:56320
	global_load_lds_dwordx4 v[206:207], off
	s_add_i32 m0, s24, 0x2000
	s_add_u32 s22, s22, 0x40080
	v_lshl_add_u64 v[206:207], v[218:219], 0, s[6:7]
	s_addc_u32 s23, s23, 0
	s_add_i32 s24, s50, s28
	global_load_lds_dwordx4 v[206:207], off
	v_lshl_add_u64 v[206:207], s[22:23], 0, v[132:133]
	s_mov_b32 m0, s24
	s_nop 0
	global_load_lds_dwordx4 v[206:207], off
	v_lshl_add_u64 v[206:207], s[22:23], 0, v[128:129]
	s_add_i32 m0, s24, 0x2000
	s_nop 0
	global_load_lds_dwordx4 v[206:207], off
	v_lshl_add_u64 v[206:207], v[220:221], 0, s[6:7]
	s_mov_b32 m0, s36
	s_nop 0
	global_load_lds_dwordx4 v[206:207], off
	v_lshl_add_u64 v[206:207], v[222:223], 0, s[6:7]
	s_mov_b32 m0, s37
	s_nop 0
	global_load_lds_dwordx4 v[206:207], off
	s_waitcnt vmcnt(8)
	s_waitcnt lgkmcnt(0)
	s_barrier
	s_setprio 1
	s_waitcnt lgkmcnt(0)
	v_mfma_f32_16x16x32_bf16 v[60:63], v[150:153], v[182:185], v[60:63]
	v_mfma_f32_16x16x32_bf16 v[56:59], v[158:161], v[182:185], v[56:59]
	v_mfma_f32_16x16x32_bf16 v[44:47], v[150:153], v[190:193], v[44:47]
	v_mfma_f32_16x16x32_bf16 v[40:43], v[158:161], v[190:193], v[40:43]
	v_mfma_f32_16x16x32_bf16 v[28:31], v[150:153], v[198:201], v[28:31]
	v_mfma_f32_16x16x32_bf16 v[24:27], v[158:161], v[198:201], v[24:27]
	v_mfma_f32_16x16x32_bf16 v[12:15], v[150:153], v[210:213], v[12:15]
	v_mfma_f32_16x16x32_bf16 v[8:11], v[158:161], v[210:213], v[8:11]
	v_mfma_f32_16x16x32_bf16 v[60:63], v[154:157], v[186:189], v[60:63]
	v_mfma_f32_16x16x32_bf16 v[56:59], v[162:165], v[186:189], v[56:59]
	v_mfma_f32_16x16x32_bf16 v[44:47], v[154:157], v[194:197], v[44:47]
	v_mfma_f32_16x16x32_bf16 v[40:43], v[162:165], v[194:197], v[40:43]
	v_mfma_f32_16x16x32_bf16 v[28:31], v[154:157], v[202:205], v[28:31]
	v_mfma_f32_16x16x32_bf16 v[24:27], v[162:165], v[202:205], v[24:27]
	v_mfma_f32_16x16x32_bf16 v[12:15], v[154:157], v[214:217], v[12:15]
	v_mfma_f32_16x16x32_bf16 v[8:11], v[162:165], v[214:217], v[8:11]
	v_mfma_f32_16x16x32_bf16 v[52:55], v[166:169], v[182:185], v[52:55]
	v_mfma_f32_16x16x32_bf16 v[48:51], v[174:177], v[182:185], v[48:51]
	v_mfma_f32_16x16x32_bf16 v[36:39], v[166:169], v[190:193], v[36:39]
	v_mfma_f32_16x16x32_bf16 v[32:35], v[174:177], v[190:193], v[32:35]
	v_mfma_f32_16x16x32_bf16 v[20:23], v[166:169], v[198:201], v[20:23]
	v_mfma_f32_16x16x32_bf16 v[16:19], v[174:177], v[198:201], v[16:19]
	v_mfma_f32_16x16x32_bf16 v[4:7], v[166:169], v[210:213], v[4:7]
	v_mfma_f32_16x16x32_bf16 v[0:3], v[174:177], v[210:213], v[0:3]
	v_mfma_f32_16x16x32_bf16 v[52:55], v[170:173], v[186:189], v[52:55]
	v_mfma_f32_16x16x32_bf16 v[48:51], v[178:181], v[186:189], v[48:51]
	v_mfma_f32_16x16x32_bf16 v[36:39], v[170:173], v[194:197], v[36:39]
	v_mfma_f32_16x16x32_bf16 v[32:35], v[178:181], v[194:197], v[32:35]
	v_mfma_f32_16x16x32_bf16 v[20:23], v[170:173], v[202:205], v[20:23]
	v_mfma_f32_16x16x32_bf16 v[16:19], v[178:181], v[202:205], v[16:19]
	v_mfma_f32_16x16x32_bf16 v[4:7], v[170:173], v[214:217], v[4:7]
	v_mfma_f32_16x16x32_bf16 v[0:3], v[178:181], v[214:217], v[0:3]
	s_setprio 0
	s_barrier
	s_add_i32 s48, s48, 2
	s_add_u32 s20, s20, 0x100
	s_addc_u32 s21, s21, 0
	s_add_u32 s46, s46, 0x100
	s_addc_u32 s47, s47, 0
	s_cmp_gt_u32 s48, 13
	s_cbranch_scc0 .LBB0_237
	s_and_b64 vcc, exec, s[8:9]
	s_cbranch_vccz .LBB0_240
	s_barrier

.LBB0_324:
	ds_read_b128 v[128:131], v240
	ds_read_b128 v[132:135], v240 offset:1024
	ds_read_b128 v[136:139], v240 offset:2048
	ds_read_b128 v[140:143], v240 offset:3072
	ds_read_b128 v[144:147], v241
	ds_read_b128 v[148:151], v241 offset:1024
	ds_read_b128 v[152:155], v241 offset:2048
	ds_read_b128 v[156:159], v241 offset:3072
	s_add_u32 s18, s4, 0xfff50080
	s_addc_u32 s19, s5, -1
	s_cmp_eq_u32 s44, 40
	s_cselect_b32 s21, s17, s19
	s_cselect_b32 s20, s16, s18
	s_cselect_b32 s19, s7, s43
	s_cselect_b32 s18, s6, s42
	v_lshl_add_u64 v[192:193], s[4:5], 0, v[218:219]
	s_add_i32 m0, s27, 0xc000
	ds_read_b128 v[160:163], v242
	ds_read_b128 v[164:167], v242 offset:1024
	ds_read_b128 v[168:171], v242 offset:2048
	ds_read_b128 v[172:175], v242 offset:3072
	ds_read_b128 v[176:179], v242 offset:4096
	ds_read_b128 v[180:183], v242 offset:5120
	ds_read_b128 v[184:187], v242 offset:6144
	ds_read_b128 v[188:191], v242 offset:7168
	global_load_lds_dwordx4 v[192:193], off
	v_lshl_add_u64 v[192:193], s[4:5], 0, v[220:221]
	s_add_i32 m0, s27, 0xe000
	s_nop 0
	global_load_lds_dwordx4 v[192:193], off
	s_waitcnt vmcnt(8)
	s_waitcnt lgkmcnt(0)
	s_barrier
	s_setprio 1
	s_waitcnt lgkmcnt(0)
	v_mfma_f32_16x16x32_bf16 v[124:127], v[128:131], v[160:163], v[124:127]
	v_mfma_f32_16x16x32_bf16 v[120:123], v[136:139], v[160:163], v[120:123]
	v_mfma_f32_16x16x32_bf16 v[116:119], v[128:131], v[168:171], v[116:119]
	v_mfma_f32_16x16x32_bf16 v[112:115], v[136:139], v[168:171], v[112:115]
	v_mfma_f32_16x16x32_bf16 v[108:111], v[128:131], v[176:179], v[108:111]
	v_mfma_f32_16x16x32_bf16 v[100:103], v[136:139], v[176:179], v[100:103]
	v_mfma_f32_16x16x32_bf16 v[80:83], v[128:131], v[184:187], v[80:83]
	v_mfma_f32_16x16x32_bf16 v[72:75], v[136:139], v[184:187], v[72:75]
	v_mfma_f32_16x16x32_bf16 v[124:127], v[132:135], v[164:167], v[124:127]
	v_mfma_f32_16x16x32_bf16 v[120:123], v[140:143], v[164:167], v[120:123]
	v_mfma_f32_16x16x32_bf16 v[116:119], v[132:135], v[172:175], v[116:119]
	v_mfma_f32_16x16x32_bf16 v[112:115], v[140:143], v[172:175], v[112:115]
	v_mfma_f32_16x16x32_bf16 v[108:111], v[132:135], v[180:183], v[108:111]
	v_mfma_f32_16x16x32_bf16 v[100:103], v[140:143], v[180:183], v[100:103]
	v_mfma_f32_16x16x32_bf16 v[80:83], v[132:135], v[188:191], v[80:83]
	v_mfma_f32_16x16x32_bf16 v[72:75], v[140:143], v[188:191], v[72:75]
	v_mfma_f32_16x16x32_bf16 v[104:107], v[144:147], v[160:163], v[104:107]
	v_mfma_f32_16x16x32_bf16 v[96:99], v[152:155], v[160:163], v[96:99]
	v_mfma_f32_16x16x32_bf16 v[92:95], v[144:147], v[168:171], v[92:95]
	v_mfma_f32_16x16x32_bf16 v[88:91], v[152:155], v[168:171], v[88:91]
	v_mfma_f32_16x16x32_bf16 v[84:87], v[144:147], v[176:179], v[84:87]
	v_mfma_f32_16x16x32_bf16 v[76:79], v[152:155], v[176:179], v[76:79]
	v_mfma_f32_16x16x32_bf16 v[68:71], v[144:147], v[184:187], v[68:71]
	v_mfma_f32_16x16x32_bf16 v[64:67], v[152:155], v[184:187], v[64:67]
	v_mfma_f32_16x16x32_bf16 v[104:107], v[148:151], v[164:167], v[104:107]
	v_mfma_f32_16x16x32_bf16 v[96:99], v[156:159], v[164:167], v[96:99]
	v_mfma_f32_16x16x32_bf16 v[92:95], v[148:151], v[172:175], v[92:95]
	v_mfma_f32_16x16x32_bf16 v[88:91], v[156:159], v[172:175], v[88:91]
	v_mfma_f32_16x16x32_bf16 v[84:87], v[148:151], v[180:183], v[84:87]
	v_mfma_f32_16x16x32_bf16 v[76:79], v[156:159], v[180:183], v[76:79]
	v_mfma_f32_16x16x32_bf16 v[68:71], v[148:151], v[188:191], v[68:71]
	v_mfma_f32_16x16x32_bf16 v[64:67], v[156:159], v[188:191], v[64:67]
	s_setprio 0
	s_barrier
	s_add_i32 s45, s38, s26
	v_lshl_add_u64 v[192:193], s[18:19], 0, v[212:213]
	s_mov_b32 m0, s45
	ds_read_b128 v[160:163], v242 offset:16384
	ds_read_b128 v[164:167], v242 offset:17408
	ds_read_b128 v[168:171], v242 offset:18432
	ds_read_b128 v[172:175], v242 offset:19456
	ds_read_b128 v[176:179], v242 offset:20480
	ds_read_b128 v[180:183], v242 offset:21504
	ds_read_b128 v[184:187], v242 offset:22528
	ds_read_b128 v[188:191], v242 offset:23552
	global_load_lds_dwordx4 v[192:193], off
	s_add_i32 m0, s45, 0x2000
	s_add_u32 s46, s18, 0xb0000
	v_lshl_add_u64 v[194:195], s[18:19], 0, v[216:217]
	s_addc_u32 s47, s19, 0
	s_add_i32 s45, s39, s26
	global_load_lds_dwordx4 v[194:195], off
	v_lshl_add_u64 v[196:197], s[46:47], 0, v[212:213]
	s_mov_b32 m0, s45
	v_lshl_add_u64 v[198:199], s[20:21], 0, v[214:215]
	global_load_lds_dwordx4 v[196:197], off
	v_lshl_add_u64 v[196:197], s[46:47], 0, v[216:217]
	s_add_i32 m0, s45, 0x2000
	s_nop 0
	global_load_lds_dwordx4 v[196:197], off
	v_lshl_add_u64 v[196:197], s[20:21], 0, v[210:211]
	s_mov_b32 m0, s27
	s_nop 0
	global_load_lds_dwordx4 v[196:197], off
	s_mov_b32 m0, s28
	s_nop 0
	global_load_lds_dwordx4 v[198:199], off
	s_waitcnt vmcnt(8)
	s_waitcnt lgkmcnt(0)
	s_barrier
	s_setprio 1
	s_waitcnt lgkmcnt(0)
	v_mfma_f32_16x16x32_bf16 v[60:63], v[128:131], v[160:163], v[60:63]
	v_mfma_f32_16x16x32_bf16 v[56:59], v[136:139], v[160:163], v[56:59]
	v_mfma_f32_16x16x32_bf16 v[52:55], v[128:131], v[168:171], v[52:55]
	v_mfma_f32_16x16x32_bf16 v[48:51], v[136:139], v[168:171], v[48:51]
	v_mfma_f32_16x16x32_bf16 v[44:47], v[128:131], v[176:179], v[44:47]
	v_mfma_f32_16x16x32_bf16 v[36:39], v[136:139], v[176:179], v[36:39]
	v_mfma_f32_16x16x32_bf16 v[20:23], v[128:131], v[184:187], v[20:23]
	v_mfma_f32_16x16x32_bf16 v[12:15], v[136:139], v[184:187], v[12:15]
	v_mfma_f32_16x16x32_bf16 v[60:63], v[132:135], v[164:167], v[60:63]
	v_mfma_f32_16x16x32_bf16 v[56:59], v[140:143], v[164:167], v[56:59]
	v_mfma_f32_16x16x32_bf16 v[52:55], v[132:135], v[172:175], v[52:55]
	v_mfma_f32_16x16x32_bf16 v[48:51], v[140:143], v[172:175], v[48:51]
	v_mfma_f32_16x16x32_bf16 v[44:47], v[132:135], v[180:183], v[44:47]
	v_mfma_f32_16x16x32_bf16 v[36:39], v[140:143], v[180:183], v[36:39]
	v_mfma_f32_16x16x32_bf16 v[20:23], v[132:135], v[188:191], v[20:23]
	v_mfma_f32_16x16x32_bf16 v[12:15], v[140:143], v[188:191], v[12:15]
	v_mfma_f32_16x16x32_bf16 v[40:43], v[144:147], v[160:163], v[40:43]
	v_mfma_f32_16x16x32_bf16 v[32:35], v[152:155], v[160:163], v[32:35]
	v_mfma_f32_16x16x32_bf16 v[28:31], v[144:147], v[168:171], v[28:31]
	v_mfma_f32_16x16x32_bf16 v[24:27], v[152:155], v[168:171], v[24:27]
	v_mfma_f32_16x16x32_bf16 v[16:19], v[144:147], v[176:179], v[16:19]
	v_mfma_f32_16x16x32_bf16 v[8:11], v[152:155], v[176:179], v[8:11]
	v_mfma_f32_16x16x32_bf16 v[4:7], v[144:147], v[184:187], v[4:7]
	v_mfma_f32_16x16x32_bf16 v[0:3], v[152:155], v[184:187], v[0:3]
	v_mfma_f32_16x16x32_bf16 v[40:43], v[148:151], v[164:167], v[40:43]
	v_mfma_f32_16x16x32_bf16 v[32:35], v[156:159], v[164:167], v[32:35]
	v_mfma_f32_16x16x32_bf16 v[28:31], v[148:151], v[172:175], v[28:31]
	v_mfma_f32_16x16x32_bf16 v[24:27], v[156:159], v[172:175], v[24:27]
	v_mfma_f32_16x16x32_bf16 v[16:19], v[148:151], v[180:183], v[16:19]
	v_mfma_f32_16x16x32_bf16 v[8:11], v[156:159], v[180:183], v[8:11]
	v_mfma_f32_16x16x32_bf16 v[4:7], v[148:151], v[188:191], v[4:7]
	v_mfma_f32_16x16x32_bf16 v[0:3], v[156:159], v[188:191], v[0:3]
	s_setprio 0
	s_barrier
	s_add_i32 s45, 0, 0x18000
	s_add_i32 s46, 0, 0x1c000
	v_add_u32_e32 v140, s45, v238
	v_add_u32_e32 v156, s46, v238
	ds_read_b128 v[128:131], v140
	ds_read_b128 v[132:135], v140 offset:1024
	ds_read_b128 v[136:139], v140 offset:2048
	ds_read_b128 v[140:143], v140 offset:3072
	ds_read_b128 v[144:147], v156
	ds_read_b128 v[148:151], v156 offset:1024
	ds_read_b128 v[152:155], v156 offset:2048
	ds_read_b128 v[156:159], v156 offset:3072
	s_add_u32 s20, s20, 0xb0000
	s_addc_u32 s21, s21, 0
	s_mov_b32 m0, s29
	v_lshl_add_u64 v[200:201], s[20:21], 0, v[210:211]
	ds_read_b128 v[160:163], v242 offset:32768
	ds_read_b128 v[164:167], v242 offset:33792
	ds_read_b128 v[168:171], v242 offset:34816
	ds_read_b128 v[172:175], v242 offset:35840
	ds_read_b128 v[176:179], v242 offset:36864
	ds_read_b128 v[180:183], v242 offset:37888
	ds_read_b128 v[184:187], v242 offset:38912
	ds_read_b128 v[188:191], v242 offset:39936
	global_load_lds_dwordx4 v[200:201], off
	v_lshl_add_u64 v[200:201], s[20:21], 0, v[214:215]
	s_mov_b32 m0, s30
	s_nop 0
	global_load_lds_dwordx4 v[200:201], off
	s_waitcnt vmcnt(8)
	s_waitcnt lgkmcnt(0)
	s_barrier
	s_setprio 1
	s_waitcnt lgkmcnt(0)
	v_mfma_f32_16x16x32_bf16 v[124:127], v[128:131], v[160:163], v[124:127]
	v_mfma_f32_16x16x32_bf16 v[120:123], v[136:139], v[160:163], v[120:123]
	v_mfma_f32_16x16x32_bf16 v[116:119], v[128:131], v[168:171], v[116:119]
	v_mfma_f32_16x16x32_bf16 v[112:115], v[136:139], v[168:171], v[112:115]
	v_mfma_f32_16x16x32_bf16 v[108:111], v[128:131], v[176:179], v[108:111]
	v_mfma_f32_16x16x32_bf16 v[100:103], v[136:139], v[176:179], v[100:103]
	v_mfma_f32_16x16x32_bf16 v[80:83], v[128:131], v[184:187], v[80:83]
	v_mfma_f32_16x16x32_bf16 v[72:75], v[136:139], v[184:187], v[72:75]
	v_mfma_f32_16x16x32_bf16 v[124:127], v[132:135], v[164:167], v[124:127]
	v_mfma_f32_16x16x32_bf16 v[120:123], v[140:143], v[164:167], v[120:123]
	v_mfma_f32_16x16x32_bf16 v[116:119], v[132:135], v[172:175], v[116:119]
	v_mfma_f32_16x16x32_bf16 v[112:115], v[140:143], v[172:175], v[112:115]
	v_mfma_f32_16x16x32_bf16 v[108:111], v[132:135], v[180:183], v[108:111]
	v_mfma_f32_16x16x32_bf16 v[100:103], v[140:143], v[180:183], v[100:103]
	v_mfma_f32_16x16x32_bf16 v[80:83], v[132:135], v[188:191], v[80:83]
	v_mfma_f32_16x16x32_bf16 v[72:75], v[140:143], v[188:191], v[72:75]
	v_mfma_f32_16x16x32_bf16 v[104:107], v[144:147], v[160:163], v[104:107]
	v_mfma_f32_16x16x32_bf16 v[96:99], v[152:155], v[160:163], v[96:99]
	v_mfma_f32_16x16x32_bf16 v[92:95], v[144:147], v[168:171], v[92:95]
	v_mfma_f32_16x16x32_bf16 v[88:91], v[152:155], v[168:171], v[88:91]
	v_mfma_f32_16x16x32_bf16 v[84:87], v[144:147], v[176:179], v[84:87]
	v_mfma_f32_16x16x32_bf16 v[76:79], v[152:155], v[176:179], v[76:79]
	v_mfma_f32_16x16x32_bf16 v[68:71], v[144:147], v[184:187], v[68:71]
	v_mfma_f32_16x16x32_bf16 v[64:67], v[152:155], v[184:187], v[64:67]
	v_mfma_f32_16x16x32_bf16 v[104:107], v[148:151], v[164:167], v[104:107]
	v_mfma_f32_16x16x32_bf16 v[96:99], v[156:159], v[164:167], v[96:99]
	v_mfma_f32_16x16x32_bf16 v[92:95], v[148:151], v[172:175], v[92:95]
	v_mfma_f32_16x16x32_bf16 v[88:91], v[156:159], v[172:175], v[88:91]
	v_mfma_f32_16x16x32_bf16 v[84:87], v[148:151], v[180:183], v[84:87]
	v_mfma_f32_16x16x32_bf16 v[76:79], v[156:159], v[180:183], v[76:79]
	v_mfma_f32_16x16x32_bf16 v[68:71], v[148:151], v[188:191], v[68:71]
	v_mfma_f32_16x16x32_bf16 v[64:67], v[156:159], v[188:191], v[64:67]
	s_setprio 0
	s_barrier
	s_add_i32 s20, s45, s26
	v_lshl_add_u64 v[192:193], v[192:193], 0, s[14:15]
	s_mov_b32 m0, s20
	ds_read_b128 v[160:163], v242 offset:49152
	ds_read_b128 v[164:167], v242 offset:50176
	ds_read_b128 v[168:171], v242 offset:51200
	ds_read_b128 v[172:175], v242 offset:52224
	ds_read_b128 v[176:179], v242 offset:53248
	ds_read_b128 v[180:183], v242 offset:54272
	ds_read_b128 v[184:187], v242 offset:55296
	ds_read_b128 v[188:191], v242 offset:56320
	global_load_lds_dwordx4 v[192:193], off
	s_add_i32 m0, s20, 0x2000
	s_add_u32 s18, s18, 0xb0080
	v_lshl_add_u64 v[192:193], v[194:195], 0, s[14:15]
	s_addc_u32 s19, s19, 0
	s_add_i32 s20, s46, s26
	global_load_lds_dwordx4 v[192:193], off
	v_lshl_add_u64 v[192:193], s[18:19], 0, v[212:213]
	s_mov_b32 m0, s20
	s_nop 0
	global_load_lds_dwordx4 v[192:193], off
	v_lshl_add_u64 v[192:193], s[18:19], 0, v[216:217]
	s_add_i32 m0, s20, 0x2000
	s_nop 0
	global_load_lds_dwordx4 v[192:193], off
	v_lshl_add_u64 v[192:193], v[196:197], 0, s[14:15]
	s_mov_b32 m0, s33
	s_nop 0
	global_load_lds_dwordx4 v[192:193], off
	v_lshl_add_u64 v[192:193], v[198:199], 0, s[14:15]
	s_mov_b32 m0, s34
	s_nop 0
	global_load_lds_dwordx4 v[192:193], off
	s_waitcnt vmcnt(8)
	s_waitcnt lgkmcnt(0)
	s_barrier
	s_setprio 1
	s_waitcnt lgkmcnt(0)
	v_mfma_f32_16x16x32_bf16 v[60:63], v[128:131], v[160:163], v[60:63]
	v_mfma_f32_16x16x32_bf16 v[56:59], v[136:139], v[160:163], v[56:59]
	v_mfma_f32_16x16x32_bf16 v[52:55], v[128:131], v[168:171], v[52:55]
	v_mfma_f32_16x16x32_bf16 v[48:51], v[136:139], v[168:171], v[48:51]
	v_mfma_f32_16x16x32_bf16 v[44:47], v[128:131], v[176:179], v[44:47]
	v_mfma_f32_16x16x32_bf16 v[36:39], v[136:139], v[176:179], v[36:39]
	v_mfma_f32_16x16x32_bf16 v[20:23], v[128:131], v[184:187], v[20:23]
	v_mfma_f32_16x16x32_bf16 v[12:15], v[136:139], v[184:187], v[12:15]
	v_mfma_f32_16x16x32_bf16 v[60:63], v[132:135], v[164:167], v[60:63]
	v_mfma_f32_16x16x32_bf16 v[56:59], v[140:143], v[164:167], v[56:59]
	v_mfma_f32_16x16x32_bf16 v[52:55], v[132:135], v[172:175], v[52:55]
	v_mfma_f32_16x16x32_bf16 v[48:51], v[140:143], v[172:175], v[48:51]
	v_mfma_f32_16x16x32_bf16 v[44:47], v[132:135], v[180:183], v[44:47]
	v_mfma_f32_16x16x32_bf16 v[36:39], v[140:143], v[180:183], v[36:39]
	v_mfma_f32_16x16x32_bf16 v[20:23], v[132:135], v[188:191], v[20:23]
	v_mfma_f32_16x16x32_bf16 v[12:15], v[140:143], v[188:191], v[12:15]
	v_mfma_f32_16x16x32_bf16 v[40:43], v[144:147], v[160:163], v[40:43]
	v_mfma_f32_16x16x32_bf16 v[32:35], v[152:155], v[160:163], v[32:35]
	v_mfma_f32_16x16x32_bf16 v[28:31], v[144:147], v[168:171], v[28:31]
	v_mfma_f32_16x16x32_bf16 v[24:27], v[152:155], v[168:171], v[24:27]
	v_mfma_f32_16x16x32_bf16 v[16:19], v[144:147], v[176:179], v[16:19]
	v_mfma_f32_16x16x32_bf16 v[8:11], v[152:155], v[176:179], v[8:11]
	v_mfma_f32_16x16x32_bf16 v[4:7], v[144:147], v[184:187], v[4:7]
	v_mfma_f32_16x16x32_bf16 v[0:3], v[152:155], v[184:187], v[0:3]
	v_mfma_f32_16x16x32_bf16 v[40:43], v[148:151], v[164:167], v[40:43]
	v_mfma_f32_16x16x32_bf16 v[32:35], v[156:159], v[164:167], v[32:35]
	v_mfma_f32_16x16x32_bf16 v[28:31], v[148:151], v[172:175], v[28:31]
	v_mfma_f32_16x16x32_bf16 v[24:27], v[156:159], v[172:175], v[24:27]
	v_mfma_f32_16x16x32_bf16 v[16:19], v[148:151], v[180:183], v[16:19]
	v_mfma_f32_16x16x32_bf16 v[8:11], v[156:159], v[180:183], v[8:11]
	v_mfma_f32_16x16x32_bf16 v[4:7], v[148:151], v[188:191], v[4:7]
	v_mfma_f32_16x16x32_bf16 v[0:3], v[156:159], v[188:191], v[0:3]
	s_setprio 0
	s_barrier
	s_add_i32 s44, s44, 2
	s_add_u32 s4, s4, 0x100
	s_addc_u32 s5, s5, 0
	s_add_u32 s42, s42, 0x100
	s_addc_u32 s43, s43, 0
	s_cmp_gt_u32 s44, 41
	s_cbranch_scc0 .LBB0_324
	s_cmp_gt_i32 s22, 63
	s_cselect_b64 s[18:19], -1, 0
	s_lshl_b32 s4, s22, 2
	s_add_i32 s43, s35, s4
	s_ashr_i32 s42, s22, 3
	s_cmp_lt_i32 s22, 64
	s_cselect_b64 s[4:5], -1, 0
	s_and_b64 vcc, s[4:5], exec
	s_cselect_b32 s20, s42, s43
	v_readlane_b32 s44, v246, 21
	v_lshl_or_b32 v128, s23, 8, v239
	v_lshl_add_u32 v228, s22, 8, v237
	s_mul_i32 s22, s20, 0x9000
	v_readlane_b32 s45, v246, 22
	v_readlane_b32 s46, v246, 23
	v_readlane_b32 s47, v246, 24
	v_ashrrev_i32_e32 v129, 31, v128
	v_add_u32_e32 v130, 0xffffc000, v228
	s_mul_hi_i32 s23, s20, 0x9000
	s_cselect_b32 s21, s45, s47
	s_cselect_b32 s20, s44, s46
	s_add_u32 s22, s10, s22
	v_or_b32_e32 v230, 16, v228
	v_add_u32_e32 v140, 0xffffc010, v228
	v_or_b32_e32 v232, 32, v228
	v_add_u32_e32 v156, 0xffffc020, v228
	v_cndmask_b32_e64 v130, v130, v228, s[4:5]
	s_addc_u32 s23, s11, s23
	v_lshlrev_b64 v[226:227], 2, v[128:129]
	v_cndmask_b32_e64 v140, v140, v230, s[4:5]
	v_cndmask_b32_e64 v156, v156, v232, s[4:5]
	v_lshl_add_u64 v[128:129], s[22:23], 0, v[226:227]
	v_ashrrev_i32_e32 v131, 31, v130
	v_ashrrev_i32_e32 v141, 31, v140
	v_ashrrev_i32_e32 v157, 31, v156
	global_load_dwordx4 v[196:199], v[128:129], off offset:16
	global_load_dwordx4 v[204:207], v[128:129], off
	global_load_dwordx4 v[192:195], v[128:129], off offset:528
	global_load_dwordx4 v[200:203], v[128:129], off offset:512
	v_lshlrev_b64 v[128:129], 12, v[130:131]
	v_lshlrev_b64 v[140:141], 12, v[140:141]
	v_lshlrev_b64 v[156:157], 12, v[156:157]
	v_lshl_add_u64 v[128:129], s[20:21], 0, v[128:129]
	v_lshl_add_u64 v[140:141], s[20:21], 0, v[140:141]
	v_lshl_add_u64 v[156:157], s[20:21], 0, v[156:157]
	v_lshl_add_u64 v[136:137], v[128:129], 0, v[226:227]
	v_lshl_add_u64 v[152:153], v[140:141], 0, v[226:227]
	v_lshl_add_u64 v[168:169], v[156:157], 0, v[226:227]
	global_load_dwordx4 v[132:135], v[136:137], off offset:16 nt
	global_load_dwordx4 v[144:147], v[136:137], off nt
	global_load_dwordx4 v[128:131], v[136:137], off offset:528 nt
	s_nop 0
	global_load_dwordx4 v[136:139], v[136:137], off offset:512 nt
	s_nop 0
	global_load_dwordx4 v[148:151], v[152:153], off offset:16 nt
	global_load_dwordx4 v[160:163], v[152:153], off nt
	global_load_dwordx4 v[140:143], v[152:153], off offset:528 nt
	s_nop 0
	global_load_dwordx4 v[152:155], v[152:153], off offset:512 nt
	s_nop 0
	global_load_dwordx4 v[164:167], v[168:169], off offset:16 nt
	global_load_dwordx4 v[172:175], v[168:169], off nt
	global_load_dwordx4 v[156:159], v[168:169], off offset:528 nt
	s_nop 0
	global_load_dwordx4 v[168:171], v[168:169], off offset:512 nt
	v_or_b32_e32 v178, 48, v228
	s_mov_b64 s[22:23], -1
	v_ashrrev_i32_e32 v179, 31, v178
	v_readlane_b32 s48, v246, 25
	v_readlane_b32 s49, v246, 26
	v_readlane_b32 s50, v246, 27
	v_readlane_b32 s51, v246, 28
	v_readlane_b32 s52, v246, 29
	v_readlane_b32 s53, v246, 30
	v_readlane_b32 s54, v246, 31
	v_readlane_b32 s55, v246, 32
	v_readlane_b32 s56, v246, 33
	v_readlane_b32 s57, v246, 34
	v_readlane_b32 s58, v246, 35
	v_readlane_b32 s59, v246, 36
	s_cbranch_vccnz .LBB0_327
	v_add_u32_e32 v176, 0xffffc030, v228
	v_ashrrev_i32_e32 v177, 31, v176
	v_readlane_b32 s44, v246, 21
	v_lshlrev_b64 v[176:177], 12, v[176:177]
	v_readlane_b32 s46, v246, 23
	v_readlane_b32 s47, v246, 24
	v_lshlrev_b64 v[234:235], 12, v[178:179]
	s_mov_b64 s[22:23], 0
	v_lshl_add_u64 v[176:177], s[46:47], 0, v[176:177]
	v_readlane_b32 s45, v246, 22
	v_readlane_b32 s48, v246, 25
	v_readlane_b32 s49, v246, 26
	v_readlane_b32 s50, v246, 27
	v_readlane_b32 s51, v246, 28
	v_readlane_b32 s52, v246, 29
	v_readlane_b32 s53, v246, 30
	v_readlane_b32 s54, v246, 31
	v_readlane_b32 s55, v246, 32
	v_readlane_b32 s56, v246, 33
	v_readlane_b32 s57, v246, 34
	v_readlane_b32 s58, v246, 35
	v_readlane_b32 s59, v246, 36

.LBB0_524:
	ds_read_b128 v[128:131], v166
	ds_read_b128 v[132:135], v166 offset:1024
	ds_read_b128 v[156:159], v166 offset:2048
	ds_read_b128 v[172:175], v166 offset:3072
	ds_read_b128 v[176:179], v167
	ds_read_b128 v[180:183], v167 offset:1024
	ds_read_b128 v[184:187], v167 offset:2048
	ds_read_b128 v[188:191], v167 offset:3072
	s_add_u32 s26, s4, 0xfffc0080
	s_addc_u32 s27, s5, -1
	s_cmp_eq_u32 s53, 12
	s_cselect_b32 s29, s7, s27
	s_cselect_b32 s28, s9, s26
	s_cselect_b32 s27, s19, s31
	s_cselect_b32 s26, s21, s30
	v_lshl_add_u64 v[160:161], s[4:5], 0, v[148:149]
	s_add_i32 m0, s36, 0xc000
	ds_read_b128 v[192:195], v168
	ds_read_b128 v[196:199], v168 offset:1024
	ds_read_b128 v[200:203], v168 offset:2048
	ds_read_b128 v[204:207], v168 offset:3072
	ds_read_b128 v[210:213], v168 offset:4096
	ds_read_b128 v[214:217], v168 offset:5120
	ds_read_b128 v[218:221], v168 offset:6144
	ds_read_b128 v[222:225], v168 offset:7168
	global_load_lds_dwordx4 v[160:161], off
	v_lshl_add_u64 v[160:161], s[4:5], 0, v[150:151]
	s_add_i32 m0, s36, 0xe000
	s_nop 0
	global_load_lds_dwordx4 v[160:161], off
	s_waitcnt vmcnt(8)
	s_waitcnt lgkmcnt(0)
	s_barrier
	s_setprio 1
	s_waitcnt lgkmcnt(0)
	v_mfma_f32_16x16x32_bf16 v[124:127], v[128:131], v[192:195], v[124:127]
	v_mfma_f32_16x16x32_bf16 v[120:123], v[156:159], v[192:195], v[120:123]
	v_mfma_f32_16x16x32_bf16 v[108:111], v[128:131], v[200:203], v[108:111]
	v_mfma_f32_16x16x32_bf16 v[104:107], v[156:159], v[200:203], v[104:107]
	v_mfma_f32_16x16x32_bf16 v[92:95], v[128:131], v[210:213], v[92:95]
	v_mfma_f32_16x16x32_bf16 v[88:91], v[156:159], v[210:213], v[88:91]
	v_mfma_f32_16x16x32_bf16 v[76:79], v[128:131], v[218:221], v[76:79]
	v_mfma_f32_16x16x32_bf16 v[72:75], v[156:159], v[218:221], v[72:75]
	v_mfma_f32_16x16x32_bf16 v[124:127], v[132:135], v[196:199], v[124:127]
	v_mfma_f32_16x16x32_bf16 v[120:123], v[172:175], v[196:199], v[120:123]
	v_mfma_f32_16x16x32_bf16 v[108:111], v[132:135], v[204:207], v[108:111]
	v_mfma_f32_16x16x32_bf16 v[104:107], v[172:175], v[204:207], v[104:107]
	v_mfma_f32_16x16x32_bf16 v[92:95], v[132:135], v[214:217], v[92:95]
	v_mfma_f32_16x16x32_bf16 v[88:91], v[172:175], v[214:217], v[88:91]
	v_mfma_f32_16x16x32_bf16 v[76:79], v[132:135], v[222:225], v[76:79]
	v_mfma_f32_16x16x32_bf16 v[72:75], v[172:175], v[222:225], v[72:75]
	v_mfma_f32_16x16x32_bf16 v[116:119], v[176:179], v[192:195], v[116:119]
	v_mfma_f32_16x16x32_bf16 v[112:115], v[184:187], v[192:195], v[112:115]
	v_mfma_f32_16x16x32_bf16 v[100:103], v[176:179], v[200:203], v[100:103]
	v_mfma_f32_16x16x32_bf16 v[96:99], v[184:187], v[200:203], v[96:99]
	v_mfma_f32_16x16x32_bf16 v[84:87], v[176:179], v[210:213], v[84:87]
	v_mfma_f32_16x16x32_bf16 v[80:83], v[184:187], v[210:213], v[80:83]
	v_mfma_f32_16x16x32_bf16 v[68:71], v[176:179], v[218:221], v[68:71]
	v_mfma_f32_16x16x32_bf16 v[64:67], v[184:187], v[218:221], v[64:67]
	v_mfma_f32_16x16x32_bf16 v[116:119], v[180:183], v[196:199], v[116:119]
	v_mfma_f32_16x16x32_bf16 v[112:115], v[188:191], v[196:199], v[112:115]
	v_mfma_f32_16x16x32_bf16 v[100:103], v[180:183], v[204:207], v[100:103]
	v_mfma_f32_16x16x32_bf16 v[96:99], v[188:191], v[204:207], v[96:99]
	v_mfma_f32_16x16x32_bf16 v[84:87], v[180:183], v[214:217], v[84:87]
	v_mfma_f32_16x16x32_bf16 v[80:83], v[188:191], v[214:217], v[80:83]
	v_mfma_f32_16x16x32_bf16 v[68:71], v[180:183], v[222:225], v[68:71]
	v_mfma_f32_16x16x32_bf16 v[64:67], v[188:191], v[222:225], v[64:67]
	s_setprio 0
	s_barrier
	s_add_i32 s54, s47, s35
	v_lshl_add_u64 v[160:161], s[26:27], 0, v[138:139]
	s_mov_b32 m0, s54
	ds_read_b128 v[192:195], v168 offset:16384
	ds_read_b128 v[196:199], v168 offset:17408
	ds_read_b128 v[200:203], v168 offset:18432
	ds_read_b128 v[204:207], v168 offset:19456
	ds_read_b128 v[210:213], v168 offset:20480
	ds_read_b128 v[214:217], v168 offset:21504
	ds_read_b128 v[218:221], v168 offset:22528
	ds_read_b128 v[222:225], v168 offset:23552
	global_load_lds_dwordx4 v[160:161], off
	s_add_i32 m0, s54, 0x2000
	s_add_u32 s54, s26, 0x40000
	v_lshl_add_u64 v[226:227], s[26:27], 0, v[142:143]
	s_addc_u32 s55, s27, 0
	s_add_i32 s56, s48, s35
	global_load_lds_dwordx4 v[226:227], off
	v_lshl_add_u64 v[228:229], s[54:55], 0, v[138:139]
	s_mov_b32 m0, s56
	v_lshl_add_u64 v[230:231], s[28:29], 0, v[140:141]
	global_load_lds_dwordx4 v[228:229], off
	v_lshl_add_u64 v[228:229], s[54:55], 0, v[142:143]
	s_add_i32 m0, s56, 0x2000
	s_nop 0
	global_load_lds_dwordx4 v[228:229], off
	v_lshl_add_u64 v[228:229], s[28:29], 0, v[136:137]
	s_mov_b32 m0, s36
	s_nop 0
	global_load_lds_dwordx4 v[228:229], off
	s_mov_b32 m0, s37
	s_nop 0
	global_load_lds_dwordx4 v[230:231], off
	s_waitcnt vmcnt(8)
	s_waitcnt lgkmcnt(0)
	s_barrier
	s_setprio 1
	s_waitcnt lgkmcnt(0)
	v_mfma_f32_16x16x32_bf16 v[60:63], v[128:131], v[192:195], v[60:63]
	v_mfma_f32_16x16x32_bf16 v[56:59], v[156:159], v[192:195], v[56:59]
	v_mfma_f32_16x16x32_bf16 v[44:47], v[128:131], v[200:203], v[44:47]
	v_mfma_f32_16x16x32_bf16 v[40:43], v[156:159], v[200:203], v[40:43]
	v_mfma_f32_16x16x32_bf16 v[28:31], v[128:131], v[210:213], v[28:31]
	v_mfma_f32_16x16x32_bf16 v[24:27], v[156:159], v[210:213], v[24:27]
	v_mfma_f32_16x16x32_bf16 v[12:15], v[128:131], v[218:221], v[12:15]
	v_mfma_f32_16x16x32_bf16 v[8:11], v[156:159], v[218:221], v[8:11]
	v_mfma_f32_16x16x32_bf16 v[60:63], v[132:135], v[196:199], v[60:63]
	v_mfma_f32_16x16x32_bf16 v[56:59], v[172:175], v[196:199], v[56:59]
	v_mfma_f32_16x16x32_bf16 v[44:47], v[132:135], v[204:207], v[44:47]
	v_mfma_f32_16x16x32_bf16 v[40:43], v[172:175], v[204:207], v[40:43]
	v_mfma_f32_16x16x32_bf16 v[28:31], v[132:135], v[214:217], v[28:31]
	v_mfma_f32_16x16x32_bf16 v[24:27], v[172:175], v[214:217], v[24:27]
	v_mfma_f32_16x16x32_bf16 v[12:15], v[132:135], v[222:225], v[12:15]
	v_mfma_f32_16x16x32_bf16 v[8:11], v[172:175], v[222:225], v[8:11]
	v_mfma_f32_16x16x32_bf16 v[52:55], v[176:179], v[192:195], v[52:55]
	v_mfma_f32_16x16x32_bf16 v[48:51], v[184:187], v[192:195], v[48:51]
	v_mfma_f32_16x16x32_bf16 v[36:39], v[176:179], v[200:203], v[36:39]
	v_mfma_f32_16x16x32_bf16 v[32:35], v[184:187], v[200:203], v[32:35]
	v_mfma_f32_16x16x32_bf16 v[20:23], v[176:179], v[210:213], v[20:23]
	v_mfma_f32_16x16x32_bf16 v[16:19], v[184:187], v[210:213], v[16:19]
	v_mfma_f32_16x16x32_bf16 v[4:7], v[176:179], v[218:221], v[4:7]
	v_mfma_f32_16x16x32_bf16 v[0:3], v[184:187], v[218:221], v[0:3]
	v_mfma_f32_16x16x32_bf16 v[52:55], v[180:183], v[196:199], v[52:55]
	v_mfma_f32_16x16x32_bf16 v[48:51], v[188:191], v[196:199], v[48:51]
	v_mfma_f32_16x16x32_bf16 v[36:39], v[180:183], v[204:207], v[36:39]
	v_mfma_f32_16x16x32_bf16 v[32:35], v[188:191], v[204:207], v[32:35]
	v_mfma_f32_16x16x32_bf16 v[20:23], v[180:183], v[214:217], v[20:23]
	v_mfma_f32_16x16x32_bf16 v[16:19], v[188:191], v[214:217], v[16:19]
	v_mfma_f32_16x16x32_bf16 v[4:7], v[180:183], v[222:225], v[4:7]
	v_mfma_f32_16x16x32_bf16 v[0:3], v[188:191], v[222:225], v[0:3]
	s_setprio 0
	s_barrier
	s_add_i32 s54, 0, 0x18000
	v_add_u32_e32 v144, s54, v164
	s_add_i32 s55, 0, 0x1c000
	ds_read_b128 v[128:131], v144
	ds_read_b128 v[132:135], v144 offset:1024
	ds_read_b128 v[156:159], v144 offset:2048
	ds_read_b128 v[172:175], v144 offset:3072
	v_add_u32_e32 v144, s55, v164
	ds_read_b128 v[176:179], v144
	ds_read_b128 v[180:183], v144 offset:1024
	ds_read_b128 v[184:187], v144 offset:2048
	ds_read_b128 v[188:191], v144 offset:3072
	s_add_u32 s28, s28, 0x40000
	s_addc_u32 s29, s29, 0
	s_mov_b32 m0, s38
	v_lshl_add_u64 v[232:233], s[28:29], 0, v[136:137]
	ds_read_b128 v[192:195], v168 offset:32768
	ds_read_b128 v[196:199], v168 offset:33792
	ds_read_b128 v[200:203], v168 offset:34816
	ds_read_b128 v[204:207], v168 offset:35840
	ds_read_b128 v[210:213], v168 offset:36864
	ds_read_b128 v[214:217], v168 offset:37888
	ds_read_b128 v[218:221], v168 offset:38912
	ds_read_b128 v[222:225], v168 offset:39936
	global_load_lds_dwordx4 v[232:233], off
	v_lshl_add_u64 v[232:233], s[28:29], 0, v[140:141]
	s_mov_b32 m0, s39
	s_nop 0
	global_load_lds_dwordx4 v[232:233], off
	s_waitcnt vmcnt(8)
	s_waitcnt lgkmcnt(0)
	s_barrier
	s_setprio 1
	s_waitcnt lgkmcnt(0)
	v_mfma_f32_16x16x32_bf16 v[124:127], v[128:131], v[192:195], v[124:127]
	v_mfma_f32_16x16x32_bf16 v[120:123], v[156:159], v[192:195], v[120:123]
	v_mfma_f32_16x16x32_bf16 v[108:111], v[128:131], v[200:203], v[108:111]
	v_mfma_f32_16x16x32_bf16 v[104:107], v[156:159], v[200:203], v[104:107]
	v_mfma_f32_16x16x32_bf16 v[92:95], v[128:131], v[210:213], v[92:95]
	v_mfma_f32_16x16x32_bf16 v[88:91], v[156:159], v[210:213], v[88:91]
	v_mfma_f32_16x16x32_bf16 v[76:79], v[128:131], v[218:221], v[76:79]
	v_mfma_f32_16x16x32_bf16 v[72:75], v[156:159], v[218:221], v[72:75]
	v_mfma_f32_16x16x32_bf16 v[124:127], v[132:135], v[196:199], v[124:127]
	v_mfma_f32_16x16x32_bf16 v[120:123], v[172:175], v[196:199], v[120:123]
	v_mfma_f32_16x16x32_bf16 v[108:111], v[132:135], v[204:207], v[108:111]
	v_mfma_f32_16x16x32_bf16 v[104:107], v[172:175], v[204:207], v[104:107]
	v_mfma_f32_16x16x32_bf16 v[92:95], v[132:135], v[214:217], v[92:95]
	v_mfma_f32_16x16x32_bf16 v[88:91], v[172:175], v[214:217], v[88:91]
	v_mfma_f32_16x16x32_bf16 v[76:79], v[132:135], v[222:225], v[76:79]
	v_mfma_f32_16x16x32_bf16 v[72:75], v[172:175], v[222:225], v[72:75]
	v_mfma_f32_16x16x32_bf16 v[116:119], v[176:179], v[192:195], v[116:119]
	v_mfma_f32_16x16x32_bf16 v[112:115], v[184:187], v[192:195], v[112:115]
	v_mfma_f32_16x16x32_bf16 v[100:103], v[176:179], v[200:203], v[100:103]
	v_mfma_f32_16x16x32_bf16 v[96:99], v[184:187], v[200:203], v[96:99]
	v_mfma_f32_16x16x32_bf16 v[84:87], v[176:179], v[210:213], v[84:87]
	v_mfma_f32_16x16x32_bf16 v[80:83], v[184:187], v[210:213], v[80:83]
	v_mfma_f32_16x16x32_bf16 v[68:71], v[176:179], v[218:221], v[68:71]
	v_mfma_f32_16x16x32_bf16 v[64:67], v[184:187], v[218:221], v[64:67]
	v_mfma_f32_16x16x32_bf16 v[116:119], v[180:183], v[196:199], v[116:119]
	v_mfma_f32_16x16x32_bf16 v[112:115], v[188:191], v[196:199], v[112:115]
	v_mfma_f32_16x16x32_bf16 v[100:103], v[180:183], v[204:207], v[100:103]
	v_mfma_f32_16x16x32_bf16 v[96:99], v[188:191], v[204:207], v[96:99]
	v_mfma_f32_16x16x32_bf16 v[84:87], v[180:183], v[214:217], v[84:87]
	v_mfma_f32_16x16x32_bf16 v[80:83], v[188:191], v[214:217], v[80:83]
	v_mfma_f32_16x16x32_bf16 v[68:71], v[180:183], v[222:225], v[68:71]
	v_mfma_f32_16x16x32_bf16 v[64:67], v[188:191], v[222:225], v[64:67]
	s_setprio 0
	s_barrier
	s_add_i32 s28, s54, s35
	v_lshl_add_u64 v[160:161], v[160:161], 0, s[12:13]
	s_mov_b32 m0, s28
	ds_read_b128 v[192:195], v168 offset:49152
	ds_read_b128 v[196:199], v168 offset:50176
	ds_read_b128 v[200:203], v168 offset:51200
	ds_read_b128 v[204:207], v168 offset:52224
	ds_read_b128 v[210:213], v168 offset:53248
	ds_read_b128 v[214:217], v168 offset:54272
	ds_read_b128 v[218:221], v168 offset:55296
	ds_read_b128 v[222:225], v168 offset:56320
	global_load_lds_dwordx4 v[160:161], off
	s_add_i32 m0, s28, 0x2000
	s_add_u32 s26, s26, 0x40080
	v_lshl_add_u64 v[160:161], v[226:227], 0, s[12:13]
	s_addc_u32 s27, s27, 0
	s_add_i32 s28, s55, s35
	global_load_lds_dwordx4 v[160:161], off
	v_lshl_add_u64 v[160:161], s[26:27], 0, v[138:139]
	s_mov_b32 m0, s28
	s_nop 0
	global_load_lds_dwordx4 v[160:161], off
	v_lshl_add_u64 v[160:161], s[26:27], 0, v[142:143]
	s_add_i32 m0, s28, 0x2000
	s_nop 0
	global_load_lds_dwordx4 v[160:161], off
	v_lshl_add_u64 v[160:161], v[228:229], 0, s[12:13]
	s_mov_b32 m0, s42
	s_nop 0
	global_load_lds_dwordx4 v[160:161], off
	v_lshl_add_u64 v[160:161], v[230:231], 0, s[12:13]
	s_mov_b32 m0, s43
	s_nop 0
	global_load_lds_dwordx4 v[160:161], off
	s_waitcnt vmcnt(8)
	s_waitcnt lgkmcnt(0)
	s_barrier
	s_setprio 1
	s_waitcnt lgkmcnt(0)
	v_mfma_f32_16x16x32_bf16 v[60:63], v[128:131], v[192:195], v[60:63]
	v_mfma_f32_16x16x32_bf16 v[56:59], v[156:159], v[192:195], v[56:59]
	v_mfma_f32_16x16x32_bf16 v[44:47], v[128:131], v[200:203], v[44:47]
	v_mfma_f32_16x16x32_bf16 v[40:43], v[156:159], v[200:203], v[40:43]
	v_mfma_f32_16x16x32_bf16 v[28:31], v[128:131], v[210:213], v[28:31]
	v_mfma_f32_16x16x32_bf16 v[24:27], v[156:159], v[210:213], v[24:27]
	v_mfma_f32_16x16x32_bf16 v[12:15], v[128:131], v[218:221], v[12:15]
	v_mfma_f32_16x16x32_bf16 v[8:11], v[156:159], v[218:221], v[8:11]
	v_mfma_f32_16x16x32_bf16 v[60:63], v[132:135], v[196:199], v[60:63]
	v_mfma_f32_16x16x32_bf16 v[56:59], v[172:175], v[196:199], v[56:59]
	v_mfma_f32_16x16x32_bf16 v[44:47], v[132:135], v[204:207], v[44:47]
	v_mfma_f32_16x16x32_bf16 v[40:43], v[172:175], v[204:207], v[40:43]
	v_mfma_f32_16x16x32_bf16 v[28:31], v[132:135], v[214:217], v[28:31]
	v_mfma_f32_16x16x32_bf16 v[24:27], v[172:175], v[214:217], v[24:27]
	v_mfma_f32_16x16x32_bf16 v[12:15], v[132:135], v[222:225], v[12:15]
	v_mfma_f32_16x16x32_bf16 v[8:11], v[172:175], v[222:225], v[8:11]
	v_mfma_f32_16x16x32_bf16 v[52:55], v[176:179], v[192:195], v[52:55]
	v_mfma_f32_16x16x32_bf16 v[48:51], v[184:187], v[192:195], v[48:51]
	v_mfma_f32_16x16x32_bf16 v[36:39], v[176:179], v[200:203], v[36:39]
	v_mfma_f32_16x16x32_bf16 v[32:35], v[184:187], v[200:203], v[32:35]
	v_mfma_f32_16x16x32_bf16 v[20:23], v[176:179], v[210:213], v[20:23]
	v_mfma_f32_16x16x32_bf16 v[16:19], v[184:187], v[210:213], v[16:19]
	v_mfma_f32_16x16x32_bf16 v[4:7], v[176:179], v[218:221], v[4:7]
	v_mfma_f32_16x16x32_bf16 v[0:3], v[184:187], v[218:221], v[0:3]
	v_mfma_f32_16x16x32_bf16 v[52:55], v[180:183], v[196:199], v[52:55]
	v_mfma_f32_16x16x32_bf16 v[48:51], v[188:191], v[196:199], v[48:51]
	v_mfma_f32_16x16x32_bf16 v[36:39], v[180:183], v[204:207], v[36:39]
	v_mfma_f32_16x16x32_bf16 v[32:35], v[188:191], v[204:207], v[32:35]
	v_mfma_f32_16x16x32_bf16 v[20:23], v[180:183], v[214:217], v[20:23]
	v_mfma_f32_16x16x32_bf16 v[16:19], v[188:191], v[214:217], v[16:19]
	v_mfma_f32_16x16x32_bf16 v[4:7], v[180:183], v[222:225], v[4:7]
	v_mfma_f32_16x16x32_bf16 v[0:3], v[188:191], v[222:225], v[0:3]
	s_setprio 0
	s_barrier
	s_add_i32 s53, s53, 2
	s_add_u32 s4, s4, 0x100
	s_addc_u32 s5, s5, 0
	s_add_u32 s30, s30, 0x100
	s_addc_u32 s31, s31, 0
	s_cmp_gt_u32 s53, 13
	s_cbranch_scc0 .LBB0_524
	s_and_b64 vcc, exec, s[14:15]
	s_cbranch_vccz .LBB0_527
	s_barrier

.LBB0_1028:
	ds_read_b128 v[128:131], v240
	ds_read_b128 v[132:135], v240 offset:1024
	ds_read_b128 v[136:139], v240 offset:2048
	ds_read_b128 v[140:143], v240 offset:3072
	ds_read_b128 v[144:147], v241
	ds_read_b128 v[148:151], v241 offset:1024
	ds_read_b128 v[152:155], v241 offset:2048
	ds_read_b128 v[156:159], v241 offset:3072
	s_add_u32 s24, s22, 0xfffc0080
	s_addc_u32 s25, s23, -1
	s_cmp_eq_u32 s50, 12
	s_cselect_b32 s27, s17, s25
	s_cselect_b32 s26, s46, s24
	s_cselect_b32 s25, s15, s49
	s_cselect_b32 s24, s47, s48
	v_lshl_add_u64 v[192:193], s[22:23], 0, v[218:219]
	s_add_i32 m0, s34, 0xc000
	ds_read_b128 v[160:163], v242
	ds_read_b128 v[164:167], v242 offset:1024
	ds_read_b128 v[168:171], v242 offset:2048
	ds_read_b128 v[172:175], v242 offset:3072
	ds_read_b128 v[176:179], v242 offset:4096
	ds_read_b128 v[180:183], v242 offset:5120
	ds_read_b128 v[184:187], v242 offset:6144
	ds_read_b128 v[188:191], v242 offset:7168
	global_load_lds_dwordx4 v[192:193], off
	v_lshl_add_u64 v[192:193], s[22:23], 0, v[220:221]
	s_add_i32 m0, s34, 0xe000
	s_nop 0
	global_load_lds_dwordx4 v[192:193], off
	s_waitcnt vmcnt(8)
	s_waitcnt lgkmcnt(0)
	s_barrier
	s_setprio 1
	s_waitcnt lgkmcnt(0)
	v_mfma_f32_16x16x32_bf16 v[124:127], v[128:131], v[160:163], v[124:127]
	v_mfma_f32_16x16x32_bf16 v[120:123], v[136:139], v[160:163], v[120:123]
	v_mfma_f32_16x16x32_bf16 v[112:115], v[128:131], v[168:171], v[112:115]
	v_mfma_f32_16x16x32_bf16 v[104:107], v[136:139], v[168:171], v[104:107]
	v_mfma_f32_16x16x32_bf16 v[96:99], v[128:131], v[176:179], v[96:99]
	v_mfma_f32_16x16x32_bf16 v[88:91], v[136:139], v[176:179], v[88:91]
	v_mfma_f32_16x16x32_bf16 v[76:79], v[128:131], v[184:187], v[76:79]
	v_mfma_f32_16x16x32_bf16 v[72:75], v[136:139], v[184:187], v[72:75]
	v_mfma_f32_16x16x32_bf16 v[124:127], v[132:135], v[164:167], v[124:127]
	v_mfma_f32_16x16x32_bf16 v[120:123], v[140:143], v[164:167], v[120:123]
	v_mfma_f32_16x16x32_bf16 v[112:115], v[132:135], v[172:175], v[112:115]
	v_mfma_f32_16x16x32_bf16 v[104:107], v[140:143], v[172:175], v[104:107]
	v_mfma_f32_16x16x32_bf16 v[96:99], v[132:135], v[180:183], v[96:99]
	v_mfma_f32_16x16x32_bf16 v[88:91], v[140:143], v[180:183], v[88:91]
	v_mfma_f32_16x16x32_bf16 v[76:79], v[132:135], v[188:191], v[76:79]
	v_mfma_f32_16x16x32_bf16 v[72:75], v[140:143], v[188:191], v[72:75]
	v_mfma_f32_16x16x32_bf16 v[116:119], v[144:147], v[160:163], v[116:119]
	v_mfma_f32_16x16x32_bf16 v[108:111], v[152:155], v[160:163], v[108:111]
	v_mfma_f32_16x16x32_bf16 v[100:103], v[144:147], v[168:171], v[100:103]
	v_mfma_f32_16x16x32_bf16 v[92:95], v[152:155], v[168:171], v[92:95]
	v_mfma_f32_16x16x32_bf16 v[84:87], v[144:147], v[176:179], v[84:87]
	v_mfma_f32_16x16x32_bf16 v[80:83], v[152:155], v[176:179], v[80:83]
	v_mfma_f32_16x16x32_bf16 v[68:71], v[144:147], v[184:187], v[68:71]
	v_mfma_f32_16x16x32_bf16 v[64:67], v[152:155], v[184:187], v[64:67]
	v_mfma_f32_16x16x32_bf16 v[116:119], v[148:151], v[164:167], v[116:119]
	v_mfma_f32_16x16x32_bf16 v[108:111], v[156:159], v[164:167], v[108:111]
	v_mfma_f32_16x16x32_bf16 v[100:103], v[148:151], v[172:175], v[100:103]
	v_mfma_f32_16x16x32_bf16 v[92:95], v[156:159], v[172:175], v[92:95]
	v_mfma_f32_16x16x32_bf16 v[84:87], v[148:151], v[180:183], v[84:87]
	v_mfma_f32_16x16x32_bf16 v[80:83], v[156:159], v[180:183], v[80:83]
	v_mfma_f32_16x16x32_bf16 v[68:71], v[148:151], v[188:191], v[68:71]
	v_mfma_f32_16x16x32_bf16 v[64:67], v[156:159], v[188:191], v[64:67]
	s_setprio 0
	s_barrier
	s_add_i32 s51, s44, s33
	v_lshl_add_u64 v[192:193], s[24:25], 0, v[212:213]
	s_mov_b32 m0, s51
	ds_read_b128 v[160:163], v242 offset:16384
	ds_read_b128 v[164:167], v242 offset:17408
	ds_read_b128 v[168:171], v242 offset:18432
	ds_read_b128 v[172:175], v242 offset:19456
	ds_read_b128 v[176:179], v242 offset:20480
	ds_read_b128 v[180:183], v242 offset:21504
	ds_read_b128 v[184:187], v242 offset:22528
	ds_read_b128 v[188:191], v242 offset:23552
	global_load_lds_dwordx4 v[192:193], off
	s_add_i32 m0, s51, 0x2000
	s_add_u32 s52, s24, 0x40000
	v_lshl_add_u64 v[194:195], s[24:25], 0, v[216:217]
	s_addc_u32 s53, s25, 0
	s_add_i32 s51, s45, s33
	global_load_lds_dwordx4 v[194:195], off
	v_lshl_add_u64 v[196:197], s[52:53], 0, v[212:213]
	s_mov_b32 m0, s51
	v_lshl_add_u64 v[198:199], s[26:27], 0, v[214:215]
	global_load_lds_dwordx4 v[196:197], off
	v_lshl_add_u64 v[196:197], s[52:53], 0, v[216:217]
	s_add_i32 m0, s51, 0x2000
	s_nop 0
	global_load_lds_dwordx4 v[196:197], off
	v_lshl_add_u64 v[196:197], s[26:27], 0, v[210:211]
	s_mov_b32 m0, s34
	s_nop 0
	global_load_lds_dwordx4 v[196:197], off
	s_mov_b32 m0, s35
	s_nop 0
	global_load_lds_dwordx4 v[198:199], off
	s_waitcnt vmcnt(8)
	s_waitcnt lgkmcnt(0)
	s_barrier
	s_setprio 1
	s_waitcnt lgkmcnt(0)
	v_mfma_f32_16x16x32_bf16 v[60:63], v[128:131], v[160:163], v[60:63]
	v_mfma_f32_16x16x32_bf16 v[56:59], v[136:139], v[160:163], v[56:59]
	v_mfma_f32_16x16x32_bf16 v[48:51], v[128:131], v[168:171], v[48:51]
	v_mfma_f32_16x16x32_bf16 v[40:43], v[136:139], v[168:171], v[40:43]
	v_mfma_f32_16x16x32_bf16 v[32:35], v[128:131], v[176:179], v[32:35]
	v_mfma_f32_16x16x32_bf16 v[24:27], v[136:139], v[176:179], v[24:27]
	v_mfma_f32_16x16x32_bf16 v[12:15], v[128:131], v[184:187], v[12:15]
	v_mfma_f32_16x16x32_bf16 v[8:11], v[136:139], v[184:187], v[8:11]
	v_mfma_f32_16x16x32_bf16 v[60:63], v[132:135], v[164:167], v[60:63]
	v_mfma_f32_16x16x32_bf16 v[56:59], v[140:143], v[164:167], v[56:59]
	v_mfma_f32_16x16x32_bf16 v[48:51], v[132:135], v[172:175], v[48:51]
	v_mfma_f32_16x16x32_bf16 v[40:43], v[140:143], v[172:175], v[40:43]
	v_mfma_f32_16x16x32_bf16 v[32:35], v[132:135], v[180:183], v[32:35]
	v_mfma_f32_16x16x32_bf16 v[24:27], v[140:143], v[180:183], v[24:27]
	v_mfma_f32_16x16x32_bf16 v[12:15], v[132:135], v[188:191], v[12:15]
	v_mfma_f32_16x16x32_bf16 v[8:11], v[140:143], v[188:191], v[8:11]
	v_mfma_f32_16x16x32_bf16 v[52:55], v[144:147], v[160:163], v[52:55]
	v_mfma_f32_16x16x32_bf16 v[44:47], v[152:155], v[160:163], v[44:47]
	v_mfma_f32_16x16x32_bf16 v[36:39], v[144:147], v[168:171], v[36:39]
	v_mfma_f32_16x16x32_bf16 v[28:31], v[152:155], v[168:171], v[28:31]
	v_mfma_f32_16x16x32_bf16 v[20:23], v[144:147], v[176:179], v[20:23]
	v_mfma_f32_16x16x32_bf16 v[16:19], v[152:155], v[176:179], v[16:19]
	v_mfma_f32_16x16x32_bf16 v[4:7], v[144:147], v[184:187], v[4:7]
	v_mfma_f32_16x16x32_bf16 v[0:3], v[152:155], v[184:187], v[0:3]
	v_mfma_f32_16x16x32_bf16 v[52:55], v[148:151], v[164:167], v[52:55]
	v_mfma_f32_16x16x32_bf16 v[44:47], v[156:159], v[164:167], v[44:47]
	v_mfma_f32_16x16x32_bf16 v[36:39], v[148:151], v[172:175], v[36:39]
	v_mfma_f32_16x16x32_bf16 v[28:31], v[156:159], v[172:175], v[28:31]
	v_mfma_f32_16x16x32_bf16 v[20:23], v[148:151], v[180:183], v[20:23]
	v_mfma_f32_16x16x32_bf16 v[16:19], v[156:159], v[180:183], v[16:19]
	v_mfma_f32_16x16x32_bf16 v[4:7], v[148:151], v[188:191], v[4:7]
	v_mfma_f32_16x16x32_bf16 v[0:3], v[156:159], v[188:191], v[0:3]
	s_setprio 0
	s_barrier
	s_add_i32 s51, 0, 0x18000
	s_add_i32 s52, 0, 0x1c000
	v_add_u32_e32 v140, s51, v238
	v_add_u32_e32 v156, s52, v238
	ds_read_b128 v[128:131], v140
	ds_read_b128 v[132:135], v140 offset:1024
	ds_read_b128 v[136:139], v140 offset:2048
	ds_read_b128 v[140:143], v140 offset:3072
	ds_read_b128 v[144:147], v156
	ds_read_b128 v[148:151], v156 offset:1024
	ds_read_b128 v[152:155], v156 offset:2048
	ds_read_b128 v[156:159], v156 offset:3072
	s_add_u32 s26, s26, 0x40000
	s_addc_u32 s27, s27, 0
	s_mov_b32 m0, s36
	v_lshl_add_u64 v[200:201], s[26:27], 0, v[210:211]
	ds_read_b128 v[160:163], v242 offset:32768
	ds_read_b128 v[164:167], v242 offset:33792
	ds_read_b128 v[168:171], v242 offset:34816
	ds_read_b128 v[172:175], v242 offset:35840
	ds_read_b128 v[176:179], v242 offset:36864
	ds_read_b128 v[180:183], v242 offset:37888
	ds_read_b128 v[184:187], v242 offset:38912
	ds_read_b128 v[188:191], v242 offset:39936
	global_load_lds_dwordx4 v[200:201], off
	v_lshl_add_u64 v[200:201], s[26:27], 0, v[214:215]
	s_mov_b32 m0, s37
	s_nop 0
	global_load_lds_dwordx4 v[200:201], off
	s_waitcnt vmcnt(8)
	s_waitcnt lgkmcnt(0)
	s_barrier
	s_setprio 1
	s_waitcnt lgkmcnt(0)
	v_mfma_f32_16x16x32_bf16 v[124:127], v[128:131], v[160:163], v[124:127]
	v_mfma_f32_16x16x32_bf16 v[120:123], v[136:139], v[160:163], v[120:123]
	v_mfma_f32_16x16x32_bf16 v[112:115], v[128:131], v[168:171], v[112:115]
	v_mfma_f32_16x16x32_bf16 v[104:107], v[136:139], v[168:171], v[104:107]
	v_mfma_f32_16x16x32_bf16 v[96:99], v[128:131], v[176:179], v[96:99]
	v_mfma_f32_16x16x32_bf16 v[88:91], v[136:139], v[176:179], v[88:91]
	v_mfma_f32_16x16x32_bf16 v[76:79], v[128:131], v[184:187], v[76:79]
	v_mfma_f32_16x16x32_bf16 v[72:75], v[136:139], v[184:187], v[72:75]
	v_mfma_f32_16x16x32_bf16 v[124:127], v[132:135], v[164:167], v[124:127]
	v_mfma_f32_16x16x32_bf16 v[120:123], v[140:143], v[164:167], v[120:123]
	v_mfma_f32_16x16x32_bf16 v[112:115], v[132:135], v[172:175], v[112:115]
	v_mfma_f32_16x16x32_bf16 v[104:107], v[140:143], v[172:175], v[104:107]
	v_mfma_f32_16x16x32_bf16 v[96:99], v[132:135], v[180:183], v[96:99]
	v_mfma_f32_16x16x32_bf16 v[88:91], v[140:143], v[180:183], v[88:91]
	v_mfma_f32_16x16x32_bf16 v[76:79], v[132:135], v[188:191], v[76:79]
	v_mfma_f32_16x16x32_bf16 v[72:75], v[140:143], v[188:191], v[72:75]
	v_mfma_f32_16x16x32_bf16 v[116:119], v[144:147], v[160:163], v[116:119]
	v_mfma_f32_16x16x32_bf16 v[108:111], v[152:155], v[160:163], v[108:111]
	v_mfma_f32_16x16x32_bf16 v[100:103], v[144:147], v[168:171], v[100:103]
	v_mfma_f32_16x16x32_bf16 v[92:95], v[152:155], v[168:171], v[92:95]
	v_mfma_f32_16x16x32_bf16 v[84:87], v[144:147], v[176:179], v[84:87]
	v_mfma_f32_16x16x32_bf16 v[80:83], v[152:155], v[176:179], v[80:83]
	v_mfma_f32_16x16x32_bf16 v[68:71], v[144:147], v[184:187], v[68:71]
	v_mfma_f32_16x16x32_bf16 v[64:67], v[152:155], v[184:187], v[64:67]
	v_mfma_f32_16x16x32_bf16 v[116:119], v[148:151], v[164:167], v[116:119]
	v_mfma_f32_16x16x32_bf16 v[108:111], v[156:159], v[164:167], v[108:111]
	v_mfma_f32_16x16x32_bf16 v[100:103], v[148:151], v[172:175], v[100:103]
	v_mfma_f32_16x16x32_bf16 v[92:95], v[156:159], v[172:175], v[92:95]
	v_mfma_f32_16x16x32_bf16 v[84:87], v[148:151], v[180:183], v[84:87]
	v_mfma_f32_16x16x32_bf16 v[80:83], v[156:159], v[180:183], v[80:83]
	v_mfma_f32_16x16x32_bf16 v[68:71], v[148:151], v[188:191], v[68:71]
	v_mfma_f32_16x16x32_bf16 v[64:67], v[156:159], v[188:191], v[64:67]
	s_setprio 0
	s_barrier
	s_add_i32 s26, s51, s33
	v_lshl_add_u64 v[192:193], v[192:193], 0, s[12:13]
	s_mov_b32 m0, s26
	ds_read_b128 v[160:163], v242 offset:49152
	ds_read_b128 v[164:167], v242 offset:50176
	ds_read_b128 v[168:171], v242 offset:51200
	ds_read_b128 v[172:175], v242 offset:52224
	ds_read_b128 v[176:179], v242 offset:53248
	ds_read_b128 v[180:183], v242 offset:54272
	ds_read_b128 v[184:187], v242 offset:55296
	ds_read_b128 v[188:191], v242 offset:56320
	global_load_lds_dwordx4 v[192:193], off
	s_add_i32 m0, s26, 0x2000
	s_add_u32 s24, s24, 0x40080
	v_lshl_add_u64 v[192:193], v[194:195], 0, s[12:13]
	s_addc_u32 s25, s25, 0
	s_add_i32 s26, s52, s33
	global_load_lds_dwordx4 v[192:193], off
	v_lshl_add_u64 v[192:193], s[24:25], 0, v[212:213]
	s_mov_b32 m0, s26
	s_nop 0
	global_load_lds_dwordx4 v[192:193], off
	v_lshl_add_u64 v[192:193], s[24:25], 0, v[216:217]
	s_add_i32 m0, s26, 0x2000
	s_nop 0
	global_load_lds_dwordx4 v[192:193], off
	v_lshl_add_u64 v[192:193], v[196:197], 0, s[12:13]
	s_mov_b32 m0, s39
	s_nop 0
	global_load_lds_dwordx4 v[192:193], off
	v_lshl_add_u64 v[192:193], v[198:199], 0, s[12:13]
	s_mov_b32 m0, s40
	s_nop 0
	global_load_lds_dwordx4 v[192:193], off
	s_waitcnt vmcnt(8)
	s_waitcnt lgkmcnt(0)
	s_barrier
	s_setprio 1
	s_waitcnt lgkmcnt(0)
	v_mfma_f32_16x16x32_bf16 v[60:63], v[128:131], v[160:163], v[60:63]
	v_mfma_f32_16x16x32_bf16 v[56:59], v[136:139], v[160:163], v[56:59]
	v_mfma_f32_16x16x32_bf16 v[48:51], v[128:131], v[168:171], v[48:51]
	v_mfma_f32_16x16x32_bf16 v[40:43], v[136:139], v[168:171], v[40:43]
	v_mfma_f32_16x16x32_bf16 v[32:35], v[128:131], v[176:179], v[32:35]
	v_mfma_f32_16x16x32_bf16 v[24:27], v[136:139], v[176:179], v[24:27]
	v_mfma_f32_16x16x32_bf16 v[12:15], v[128:131], v[184:187], v[12:15]
	v_mfma_f32_16x16x32_bf16 v[8:11], v[136:139], v[184:187], v[8:11]
	v_mfma_f32_16x16x32_bf16 v[60:63], v[132:135], v[164:167], v[60:63]
	v_mfma_f32_16x16x32_bf16 v[56:59], v[140:143], v[164:167], v[56:59]
	v_mfma_f32_16x16x32_bf16 v[48:51], v[132:135], v[172:175], v[48:51]
	v_mfma_f32_16x16x32_bf16 v[40:43], v[140:143], v[172:175], v[40:43]
	v_mfma_f32_16x16x32_bf16 v[32:35], v[132:135], v[180:183], v[32:35]
	v_mfma_f32_16x16x32_bf16 v[24:27], v[140:143], v[180:183], v[24:27]
	v_mfma_f32_16x16x32_bf16 v[12:15], v[132:135], v[188:191], v[12:15]
	v_mfma_f32_16x16x32_bf16 v[8:11], v[140:143], v[188:191], v[8:11]
	v_mfma_f32_16x16x32_bf16 v[52:55], v[144:147], v[160:163], v[52:55]
	v_mfma_f32_16x16x32_bf16 v[44:47], v[152:155], v[160:163], v[44:47]
	v_mfma_f32_16x16x32_bf16 v[36:39], v[144:147], v[168:171], v[36:39]
	v_mfma_f32_16x16x32_bf16 v[28:31], v[152:155], v[168:171], v[28:31]
	v_mfma_f32_16x16x32_bf16 v[20:23], v[144:147], v[176:179], v[20:23]
	v_mfma_f32_16x16x32_bf16 v[16:19], v[152:155], v[176:179], v[16:19]
	v_mfma_f32_16x16x32_bf16 v[4:7], v[144:147], v[184:187], v[4:7]
	v_mfma_f32_16x16x32_bf16 v[0:3], v[152:155], v[184:187], v[0:3]
	v_mfma_f32_16x16x32_bf16 v[52:55], v[148:151], v[164:167], v[52:55]
	v_mfma_f32_16x16x32_bf16 v[44:47], v[156:159], v[164:167], v[44:47]
	v_mfma_f32_16x16x32_bf16 v[36:39], v[148:151], v[172:175], v[36:39]
	v_mfma_f32_16x16x32_bf16 v[28:31], v[156:159], v[172:175], v[28:31]
	v_mfma_f32_16x16x32_bf16 v[20:23], v[148:151], v[180:183], v[20:23]
	v_mfma_f32_16x16x32_bf16 v[16:19], v[156:159], v[180:183], v[16:19]
	v_mfma_f32_16x16x32_bf16 v[4:7], v[148:151], v[188:191], v[4:7]
	v_mfma_f32_16x16x32_bf16 v[0:3], v[156:159], v[188:191], v[0:3]
	s_setprio 0
	s_barrier
	s_add_i32 s50, s50, 2
	s_add_u32 s22, s22, 0x100
	s_addc_u32 s23, s23, 0
	s_add_u32 s48, s48, 0x100
	s_addc_u32 s49, s49, 0
	s_cmp_gt_u32 s50, 13
	s_cbranch_scc0 .LBB0_1028
	s_cmp_gt_i32 s4, 63
	v_lshl_or_b32 v128, s5, 8, v239
	s_cselect_b64 s[22:23], -1, 0
	s_lshl_b32 s5, s4, 2
	s_add_i32 s17, s41, s5
	s_ashr_i32 s15, s4, 3
	s_cmp_lt_i32 s4, 64
	v_lshl_add_u32 v228, s4, 8, v237
	s_cselect_b64 s[4:5], -1, 0
	v_add_u32_e32 v130, 0xffffc000, v228
	s_and_b64 vcc, s[4:5], exec
	v_cndmask_b32_e64 v144, v130, v228, s[4:5]
	s_cselect_b32 s24, s15, s17
	s_mul_i32 s26, s24, 0x9000
	v_ashrrev_i32_e32 v145, 31, v144
	v_ashrrev_i32_e32 v129, 31, v128
	s_mul_hi_i32 s27, s24, 0x9000
	s_cselect_b32 s25, s73, s7
	s_cselect_b32 s24, s72, s6
	s_add_u32 s26, s10, s26
	v_lshlrev_b64 v[144:145], 12, v[144:145]
	s_addc_u32 s27, s11, s27
	v_lshlrev_b64 v[226:227], 2, v[128:129]
	v_lshl_add_u64 v[144:145], s[24:25], 0, v[144:145]
	v_lshl_add_u64 v[136:137], s[26:27], 0, v[226:227]
	v_lshl_add_u64 v[144:145], v[144:145], 0, v[226:227]
	global_load_dwordx4 v[132:135], v[136:137], off offset:16
	global_load_dwordx4 v[140:143], v[136:137], off
	global_load_dwordx4 v[128:131], v[136:137], off offset:528
	s_nop 0
	global_load_dwordx4 v[136:139], v[136:137], off offset:512
	s_nop 0
	global_load_dwordx4 v[200:203], v[144:145], off offset:16
	global_load_dwordx4 v[204:207], v[144:145], off
	global_load_dwordx4 v[192:195], v[144:145], off offset:528
	global_load_dwordx4 v[196:199], v[144:145], off offset:512
	v_or_b32_e32 v230, 16, v228
	v_add_u32_e32 v144, 0xffffc010, v228
	v_cndmask_b32_e64 v144, v144, v230, s[4:5]
	v_ashrrev_i32_e32 v145, 31, v144
	v_lshlrev_b64 v[144:145], 12, v[144:145]
	v_lshl_add_u64 v[144:145], s[24:25], 0, v[144:145]
	v_lshl_add_u64 v[144:145], v[144:145], 0, v[226:227]
	global_load_dwordx4 v[184:187], v[144:145], off offset:16
	global_load_dwordx4 v[188:191], v[144:145], off
	global_load_dwordx4 v[176:179], v[144:145], off offset:528
	global_load_dwordx4 v[180:183], v[144:145], off offset:512
	v_or_b32_e32 v232, 32, v228
	v_add_u32_e32 v144, 0xffffc020, v228
	v_cndmask_b32_e64 v144, v144, v232, s[4:5]
	v_ashrrev_i32_e32 v145, 31, v144
	v_lshlrev_b64 v[144:145], 12, v[144:145]
	v_lshl_add_u64 v[144:145], s[24:25], 0, v[144:145]
	v_lshl_add_u64 v[144:145], v[144:145], 0, v[226:227]
	global_load_dwordx4 v[168:171], v[144:145], off offset:16
	global_load_dwordx4 v[172:175], v[144:145], off
	global_load_dwordx4 v[160:163], v[144:145], off offset:528
	global_load_dwordx4 v[164:167], v[144:145], off offset:512
	v_or_b32_e32 v146, 48, v228
	s_mov_b64 s[26:27], -1
	v_ashrrev_i32_e32 v147, 31, v146
	s_cbranch_vccnz .LBB0_1031
	v_add_u32_e32 v144, 0xffffc030, v228
	v_ashrrev_i32_e32 v145, 31, v144
	v_lshlrev_b64 v[144:145], 12, v[144:145]
	v_lshl_add_u64 v[144:145], s[6:7], 0, v[144:145]
	v_lshlrev_b64 v[234:235], 12, v[146:147]
	s_mov_b64 s[26:27], 0

.LBB0_1219:
	ds_read_b128 v[150:153], v147
	ds_read_b128 v[154:157], v147 offset:1024
	ds_read_b128 v[158:161], v147 offset:2048
	ds_read_b128 v[162:165], v147 offset:3072
	ds_read_b128 v[166:169], v148
	ds_read_b128 v[170:173], v148 offset:1024
	ds_read_b128 v[174:177], v148 offset:2048
	ds_read_b128 v[178:181], v148 offset:3072
	s_add_u32 s24, s22, 0xfffc0080
	s_addc_u32 s25, s23, -1
	s_cmp_eq_u32 s48, 12
	s_cselect_b32 s27, s15, s25
	s_cselect_b32 s26, s44, s24
	s_cselect_b32 s25, s13, s47
	s_cselect_b32 s24, s45, s46
	v_lshl_add_u64 v[206:207], s[22:23], 0, v[136:137]
	s_add_i32 m0, s21, 0xc000
	ds_read_b128 v[182:185], v149
	ds_read_b128 v[186:189], v149 offset:1024
	ds_read_b128 v[190:193], v149 offset:2048
	ds_read_b128 v[194:197], v149 offset:3072
	ds_read_b128 v[198:201], v149 offset:4096
	ds_read_b128 v[202:205], v149 offset:5120
	ds_read_b128 v[210:213], v149 offset:6144
	ds_read_b128 v[214:217], v149 offset:7168
	global_load_lds_dwordx4 v[206:207], off
	v_lshl_add_u64 v[206:207], s[22:23], 0, v[138:139]
	s_add_i32 m0, s21, 0xe000
	s_nop 0
	global_load_lds_dwordx4 v[206:207], off
	s_waitcnt vmcnt(8)
	s_waitcnt lgkmcnt(0)
	s_barrier
	s_setprio 1
	s_waitcnt lgkmcnt(0)
	v_mfma_f32_16x16x32_bf16 v[124:127], v[150:153], v[182:185], v[124:127]
	v_mfma_f32_16x16x32_bf16 v[120:123], v[158:161], v[182:185], v[120:123]
	v_mfma_f32_16x16x32_bf16 v[108:111], v[150:153], v[190:193], v[108:111]
	v_mfma_f32_16x16x32_bf16 v[104:107], v[158:161], v[190:193], v[104:107]
	v_mfma_f32_16x16x32_bf16 v[92:95], v[150:153], v[198:201], v[92:95]
	v_mfma_f32_16x16x32_bf16 v[88:91], v[158:161], v[198:201], v[88:91]
	v_mfma_f32_16x16x32_bf16 v[76:79], v[150:153], v[210:213], v[76:79]
	v_mfma_f32_16x16x32_bf16 v[72:75], v[158:161], v[210:213], v[72:75]
	v_mfma_f32_16x16x32_bf16 v[124:127], v[154:157], v[186:189], v[124:127]
	v_mfma_f32_16x16x32_bf16 v[120:123], v[162:165], v[186:189], v[120:123]
	v_mfma_f32_16x16x32_bf16 v[108:111], v[154:157], v[194:197], v[108:111]
	v_mfma_f32_16x16x32_bf16 v[104:107], v[162:165], v[194:197], v[104:107]
	v_mfma_f32_16x16x32_bf16 v[92:95], v[154:157], v[202:205], v[92:95]
	v_mfma_f32_16x16x32_bf16 v[88:91], v[162:165], v[202:205], v[88:91]
	v_mfma_f32_16x16x32_bf16 v[76:79], v[154:157], v[214:217], v[76:79]
	v_mfma_f32_16x16x32_bf16 v[72:75], v[162:165], v[214:217], v[72:75]
	v_mfma_f32_16x16x32_bf16 v[116:119], v[166:169], v[182:185], v[116:119]
	v_mfma_f32_16x16x32_bf16 v[112:115], v[174:177], v[182:185], v[112:115]
	v_mfma_f32_16x16x32_bf16 v[100:103], v[166:169], v[190:193], v[100:103]
	v_mfma_f32_16x16x32_bf16 v[96:99], v[174:177], v[190:193], v[96:99]
	v_mfma_f32_16x16x32_bf16 v[84:87], v[166:169], v[198:201], v[84:87]
	v_mfma_f32_16x16x32_bf16 v[80:83], v[174:177], v[198:201], v[80:83]
	v_mfma_f32_16x16x32_bf16 v[68:71], v[166:169], v[210:213], v[68:71]
	v_mfma_f32_16x16x32_bf16 v[64:67], v[174:177], v[210:213], v[64:67]
	v_mfma_f32_16x16x32_bf16 v[116:119], v[170:173], v[186:189], v[116:119]
	v_mfma_f32_16x16x32_bf16 v[112:115], v[178:181], v[186:189], v[112:115]
	v_mfma_f32_16x16x32_bf16 v[100:103], v[170:173], v[194:197], v[100:103]
	v_mfma_f32_16x16x32_bf16 v[96:99], v[178:181], v[194:197], v[96:99]
	v_mfma_f32_16x16x32_bf16 v[84:87], v[170:173], v[202:205], v[84:87]
	v_mfma_f32_16x16x32_bf16 v[80:83], v[178:181], v[202:205], v[80:83]
	v_mfma_f32_16x16x32_bf16 v[68:71], v[170:173], v[214:217], v[68:71]
	v_mfma_f32_16x16x32_bf16 v[64:67], v[178:181], v[214:217], v[64:67]
	s_setprio 0
	s_barrier
	s_add_i32 s49, s40, s28
	v_lshl_add_u64 v[206:207], s[24:25], 0, v[132:133]
	s_mov_b32 m0, s49
	ds_read_b128 v[182:185], v149 offset:16384
	ds_read_b128 v[186:189], v149 offset:17408
	ds_read_b128 v[190:193], v149 offset:18432
	ds_read_b128 v[194:197], v149 offset:19456
	ds_read_b128 v[198:201], v149 offset:20480
	ds_read_b128 v[202:205], v149 offset:21504
	ds_read_b128 v[210:213], v149 offset:22528
	ds_read_b128 v[214:217], v149 offset:23552
	global_load_lds_dwordx4 v[206:207], off
	s_add_i32 m0, s49, 0x2000
	s_add_u32 s50, s24, 0x40000
	v_lshl_add_u64 v[218:219], s[24:25], 0, v[128:129]
	s_addc_u32 s51, s25, 0
	s_add_i32 s49, s41, s28
	global_load_lds_dwordx4 v[218:219], off
	v_lshl_add_u64 v[220:221], s[50:51], 0, v[132:133]
	s_mov_b32 m0, s49
	v_lshl_add_u64 v[222:223], s[26:27], 0, v[130:131]
	global_load_lds_dwordx4 v[220:221], off
	v_lshl_add_u64 v[220:221], s[50:51], 0, v[128:129]
	s_add_i32 m0, s49, 0x2000
	s_nop 0
	global_load_lds_dwordx4 v[220:221], off
	v_lshl_add_u64 v[220:221], s[26:27], 0, v[134:135]
	s_mov_b32 m0, s21
	s_nop 0
	global_load_lds_dwordx4 v[220:221], off
	s_mov_b32 m0, s31
	s_nop 0
	global_load_lds_dwordx4 v[222:223], off
	s_waitcnt vmcnt(8)
	s_waitcnt lgkmcnt(0)
	s_barrier
	s_setprio 1
	s_waitcnt lgkmcnt(0)
	v_mfma_f32_16x16x32_bf16 v[60:63], v[150:153], v[182:185], v[60:63]
	v_mfma_f32_16x16x32_bf16 v[56:59], v[158:161], v[182:185], v[56:59]
	v_mfma_f32_16x16x32_bf16 v[44:47], v[150:153], v[190:193], v[44:47]
	v_mfma_f32_16x16x32_bf16 v[40:43], v[158:161], v[190:193], v[40:43]
	v_mfma_f32_16x16x32_bf16 v[28:31], v[150:153], v[198:201], v[28:31]
	v_mfma_f32_16x16x32_bf16 v[24:27], v[158:161], v[198:201], v[24:27]
	v_mfma_f32_16x16x32_bf16 v[12:15], v[150:153], v[210:213], v[12:15]
	v_mfma_f32_16x16x32_bf16 v[8:11], v[158:161], v[210:213], v[8:11]
	v_mfma_f32_16x16x32_bf16 v[60:63], v[154:157], v[186:189], v[60:63]
	v_mfma_f32_16x16x32_bf16 v[56:59], v[162:165], v[186:189], v[56:59]
	v_mfma_f32_16x16x32_bf16 v[44:47], v[154:157], v[194:197], v[44:47]
	v_mfma_f32_16x16x32_bf16 v[40:43], v[162:165], v[194:197], v[40:43]
	v_mfma_f32_16x16x32_bf16 v[28:31], v[154:157], v[202:205], v[28:31]
	v_mfma_f32_16x16x32_bf16 v[24:27], v[162:165], v[202:205], v[24:27]
	v_mfma_f32_16x16x32_bf16 v[12:15], v[154:157], v[214:217], v[12:15]
	v_mfma_f32_16x16x32_bf16 v[8:11], v[162:165], v[214:217], v[8:11]
	v_mfma_f32_16x16x32_bf16 v[52:55], v[166:169], v[182:185], v[52:55]
	v_mfma_f32_16x16x32_bf16 v[48:51], v[174:177], v[182:185], v[48:51]
	v_mfma_f32_16x16x32_bf16 v[36:39], v[166:169], v[190:193], v[36:39]
	v_mfma_f32_16x16x32_bf16 v[32:35], v[174:177], v[190:193], v[32:35]
	v_mfma_f32_16x16x32_bf16 v[20:23], v[166:169], v[198:201], v[20:23]
	v_mfma_f32_16x16x32_bf16 v[16:19], v[174:177], v[198:201], v[16:19]
	v_mfma_f32_16x16x32_bf16 v[4:7], v[166:169], v[210:213], v[4:7]
	v_mfma_f32_16x16x32_bf16 v[0:3], v[174:177], v[210:213], v[0:3]
	v_mfma_f32_16x16x32_bf16 v[52:55], v[170:173], v[186:189], v[52:55]
	v_mfma_f32_16x16x32_bf16 v[48:51], v[178:181], v[186:189], v[48:51]
	v_mfma_f32_16x16x32_bf16 v[36:39], v[170:173], v[194:197], v[36:39]
	v_mfma_f32_16x16x32_bf16 v[32:35], v[178:181], v[194:197], v[32:35]
	v_mfma_f32_16x16x32_bf16 v[20:23], v[170:173], v[202:205], v[20:23]
	v_mfma_f32_16x16x32_bf16 v[16:19], v[178:181], v[202:205], v[16:19]
	v_mfma_f32_16x16x32_bf16 v[4:7], v[170:173], v[214:217], v[4:7]
	v_mfma_f32_16x16x32_bf16 v[0:3], v[178:181], v[214:217], v[0:3]
	s_setprio 0
	s_barrier
	s_add_i32 s49, 0, 0x18000
	s_add_i32 s50, 0, 0x1c000
	v_add_u32_e32 v162, s49, v145
	v_add_u32_e32 v178, s50, v145
	ds_read_b128 v[150:153], v162
	ds_read_b128 v[154:157], v162 offset:1024
	ds_read_b128 v[158:161], v162 offset:2048
	ds_read_b128 v[162:165], v162 offset:3072
	ds_read_b128 v[166:169], v178
	ds_read_b128 v[170:173], v178 offset:1024
	ds_read_b128 v[174:177], v178 offset:2048
	ds_read_b128 v[178:181], v178 offset:3072
	s_add_u32 s26, s26, 0x40000
	s_addc_u32 s27, s27, 0
	s_mov_b32 m0, s33
	v_lshl_add_u64 v[224:225], s[26:27], 0, v[134:135]
	ds_read_b128 v[182:185], v149 offset:32768
	ds_read_b128 v[186:189], v149 offset:33792
	ds_read_b128 v[190:193], v149 offset:34816
	ds_read_b128 v[194:197], v149 offset:35840
	ds_read_b128 v[198:201], v149 offset:36864
	ds_read_b128 v[202:205], v149 offset:37888
	ds_read_b128 v[210:213], v149 offset:38912
	ds_read_b128 v[214:217], v149 offset:39936
	global_load_lds_dwordx4 v[224:225], off
	v_lshl_add_u64 v[224:225], s[26:27], 0, v[130:131]
	s_mov_b32 m0, s34
	s_nop 0
	global_load_lds_dwordx4 v[224:225], off
	s_waitcnt vmcnt(8)
	s_waitcnt lgkmcnt(0)
	s_barrier
	s_setprio 1
	s_waitcnt lgkmcnt(0)
	v_mfma_f32_16x16x32_bf16 v[124:127], v[150:153], v[182:185], v[124:127]
	v_mfma_f32_16x16x32_bf16 v[120:123], v[158:161], v[182:185], v[120:123]
	v_mfma_f32_16x16x32_bf16 v[108:111], v[150:153], v[190:193], v[108:111]
	v_mfma_f32_16x16x32_bf16 v[104:107], v[158:161], v[190:193], v[104:107]
	v_mfma_f32_16x16x32_bf16 v[92:95], v[150:153], v[198:201], v[92:95]
	v_mfma_f32_16x16x32_bf16 v[88:91], v[158:161], v[198:201], v[88:91]
	v_mfma_f32_16x16x32_bf16 v[76:79], v[150:153], v[210:213], v[76:79]
	v_mfma_f32_16x16x32_bf16 v[72:75], v[158:161], v[210:213], v[72:75]
	v_mfma_f32_16x16x32_bf16 v[124:127], v[154:157], v[186:189], v[124:127]
	v_mfma_f32_16x16x32_bf16 v[120:123], v[162:165], v[186:189], v[120:123]
	v_mfma_f32_16x16x32_bf16 v[108:111], v[154:157], v[194:197], v[108:111]
	v_mfma_f32_16x16x32_bf16 v[104:107], v[162:165], v[194:197], v[104:107]
	v_mfma_f32_16x16x32_bf16 v[92:95], v[154:157], v[202:205], v[92:95]
	v_mfma_f32_16x16x32_bf16 v[88:91], v[162:165], v[202:205], v[88:91]
	v_mfma_f32_16x16x32_bf16 v[76:79], v[154:157], v[214:217], v[76:79]
	v_mfma_f32_16x16x32_bf16 v[72:75], v[162:165], v[214:217], v[72:75]
	v_mfma_f32_16x16x32_bf16 v[116:119], v[166:169], v[182:185], v[116:119]
	v_mfma_f32_16x16x32_bf16 v[112:115], v[174:177], v[182:185], v[112:115]
	v_mfma_f32_16x16x32_bf16 v[100:103], v[166:169], v[190:193], v[100:103]
	v_mfma_f32_16x16x32_bf16 v[96:99], v[174:177], v[190:193], v[96:99]
	v_mfma_f32_16x16x32_bf16 v[84:87], v[166:169], v[198:201], v[84:87]
	v_mfma_f32_16x16x32_bf16 v[80:83], v[174:177], v[198:201], v[80:83]
	v_mfma_f32_16x16x32_bf16 v[68:71], v[166:169], v[210:213], v[68:71]
	v_mfma_f32_16x16x32_bf16 v[64:67], v[174:177], v[210:213], v[64:67]
	v_mfma_f32_16x16x32_bf16 v[116:119], v[170:173], v[186:189], v[116:119]
	v_mfma_f32_16x16x32_bf16 v[112:115], v[178:181], v[186:189], v[112:115]
	v_mfma_f32_16x16x32_bf16 v[100:103], v[170:173], v[194:197], v[100:103]
	v_mfma_f32_16x16x32_bf16 v[96:99], v[178:181], v[194:197], v[96:99]
	v_mfma_f32_16x16x32_bf16 v[84:87], v[170:173], v[202:205], v[84:87]
	v_mfma_f32_16x16x32_bf16 v[80:83], v[178:181], v[202:205], v[80:83]
	v_mfma_f32_16x16x32_bf16 v[68:71], v[170:173], v[214:217], v[68:71]
	v_mfma_f32_16x16x32_bf16 v[64:67], v[178:181], v[214:217], v[64:67]
	s_setprio 0
	s_barrier
	s_add_i32 s26, s49, s28
	v_lshl_add_u64 v[206:207], v[206:207], 0, s[8:9]
	s_mov_b32 m0, s26
	ds_read_b128 v[182:185], v149 offset:49152
	ds_read_b128 v[186:189], v149 offset:50176
	ds_read_b128 v[190:193], v149 offset:51200
	ds_read_b128 v[194:197], v149 offset:52224
	ds_read_b128 v[198:201], v149 offset:53248
	ds_read_b128 v[202:205], v149 offset:54272
	ds_read_b128 v[210:213], v149 offset:55296
	ds_read_b128 v[214:217], v149 offset:56320
	global_load_lds_dwordx4 v[206:207], off
	s_add_i32 m0, s26, 0x2000
	s_add_u32 s24, s24, 0x40080
	v_lshl_add_u64 v[206:207], v[218:219], 0, s[8:9]
	s_addc_u32 s25, s25, 0
	s_add_i32 s26, s50, s28
	global_load_lds_dwordx4 v[206:207], off
	v_lshl_add_u64 v[206:207], s[24:25], 0, v[132:133]
	s_mov_b32 m0, s26
	s_nop 0
	global_load_lds_dwordx4 v[206:207], off
	v_lshl_add_u64 v[206:207], s[24:25], 0, v[128:129]
	s_add_i32 m0, s26, 0x2000
	s_nop 0
	global_load_lds_dwordx4 v[206:207], off
	v_lshl_add_u64 v[206:207], v[220:221], 0, s[8:9]
	s_mov_b32 m0, s36
	s_nop 0
	global_load_lds_dwordx4 v[206:207], off
	v_lshl_add_u64 v[206:207], v[222:223], 0, s[8:9]
	s_mov_b32 m0, s37
	s_nop 0
	global_load_lds_dwordx4 v[206:207], off
	s_waitcnt vmcnt(8)
	s_waitcnt lgkmcnt(0)
	s_barrier
	s_setprio 1
	s_waitcnt lgkmcnt(0)
	v_mfma_f32_16x16x32_bf16 v[60:63], v[150:153], v[182:185], v[60:63]
	v_mfma_f32_16x16x32_bf16 v[56:59], v[158:161], v[182:185], v[56:59]
	v_mfma_f32_16x16x32_bf16 v[44:47], v[150:153], v[190:193], v[44:47]
	v_mfma_f32_16x16x32_bf16 v[40:43], v[158:161], v[190:193], v[40:43]
	v_mfma_f32_16x16x32_bf16 v[28:31], v[150:153], v[198:201], v[28:31]
	v_mfma_f32_16x16x32_bf16 v[24:27], v[158:161], v[198:201], v[24:27]
	v_mfma_f32_16x16x32_bf16 v[12:15], v[150:153], v[210:213], v[12:15]
	v_mfma_f32_16x16x32_bf16 v[8:11], v[158:161], v[210:213], v[8:11]
	v_mfma_f32_16x16x32_bf16 v[60:63], v[154:157], v[186:189], v[60:63]
	v_mfma_f32_16x16x32_bf16 v[56:59], v[162:165], v[186:189], v[56:59]
	v_mfma_f32_16x16x32_bf16 v[44:47], v[154:157], v[194:197], v[44:47]
	v_mfma_f32_16x16x32_bf16 v[40:43], v[162:165], v[194:197], v[40:43]
	v_mfma_f32_16x16x32_bf16 v[28:31], v[154:157], v[202:205], v[28:31]
	v_mfma_f32_16x16x32_bf16 v[24:27], v[162:165], v[202:205], v[24:27]
	v_mfma_f32_16x16x32_bf16 v[12:15], v[154:157], v[214:217], v[12:15]
	v_mfma_f32_16x16x32_bf16 v[8:11], v[162:165], v[214:217], v[8:11]
	v_mfma_f32_16x16x32_bf16 v[52:55], v[166:169], v[182:185], v[52:55]
	v_mfma_f32_16x16x32_bf16 v[48:51], v[174:177], v[182:185], v[48:51]
	v_mfma_f32_16x16x32_bf16 v[36:39], v[166:169], v[190:193], v[36:39]
	v_mfma_f32_16x16x32_bf16 v[32:35], v[174:177], v[190:193], v[32:35]
	v_mfma_f32_16x16x32_bf16 v[20:23], v[166:169], v[198:201], v[20:23]
	v_mfma_f32_16x16x32_bf16 v[16:19], v[174:177], v[198:201], v[16:19]
	v_mfma_f32_16x16x32_bf16 v[4:7], v[166:169], v[210:213], v[4:7]
	v_mfma_f32_16x16x32_bf16 v[0:3], v[174:177], v[210:213], v[0:3]
	v_mfma_f32_16x16x32_bf16 v[52:55], v[170:173], v[186:189], v[52:55]
	v_mfma_f32_16x16x32_bf16 v[48:51], v[178:181], v[186:189], v[48:51]
	v_mfma_f32_16x16x32_bf16 v[36:39], v[170:173], v[194:197], v[36:39]
	v_mfma_f32_16x16x32_bf16 v[32:35], v[178:181], v[194:197], v[32:35]
	v_mfma_f32_16x16x32_bf16 v[20:23], v[170:173], v[202:205], v[20:23]
	v_mfma_f32_16x16x32_bf16 v[16:19], v[178:181], v[202:205], v[16:19]
	v_mfma_f32_16x16x32_bf16 v[4:7], v[170:173], v[214:217], v[4:7]
	v_mfma_f32_16x16x32_bf16 v[0:3], v[178:181], v[214:217], v[0:3]
	s_setprio 0
	s_barrier
	s_add_i32 s48, s48, 2
	s_add_u32 s22, s22, 0x100
	s_addc_u32 s23, s23, 0
	s_add_u32 s46, s46, 0x100
	s_addc_u32 s47, s47, 0
	s_cmp_gt_u32 s48, 13
	s_cbranch_scc0 .LBB0_1219
	s_and_b64 vcc, exec, s[10:11]
	s_cbranch_vccz .LBB0_1222
	s_barrier

.LBB0_1318:
	ds_read_b128 v[128:131], v240
	ds_read_b128 v[132:135], v240 offset:1024
	ds_read_b128 v[136:139], v240 offset:2048
	ds_read_b128 v[140:143], v240 offset:3072
	ds_read_b128 v[144:147], v241
	ds_read_b128 v[148:151], v241 offset:1024
	ds_read_b128 v[152:155], v241 offset:2048
	ds_read_b128 v[156:159], v241 offset:3072
	s_add_u32 s20, s4, 0xfff50080
	s_addc_u32 s21, s5, -1
	s_cmp_eq_u32 s46, 40
	s_cselect_b32 s23, s19, s21
	s_cselect_b32 s22, s18, s20
	s_cselect_b32 s21, s7, s45
	s_cselect_b32 s20, s6, s44
	v_lshl_add_u64 v[192:193], s[4:5], 0, v[218:219]
	s_add_i32 m0, s29, 0xc000
	ds_read_b128 v[160:163], v242
	ds_read_b128 v[164:167], v242 offset:1024
	ds_read_b128 v[168:171], v242 offset:2048
	ds_read_b128 v[172:175], v242 offset:3072
	ds_read_b128 v[176:179], v242 offset:4096
	ds_read_b128 v[180:183], v242 offset:5120
	ds_read_b128 v[184:187], v242 offset:6144
	ds_read_b128 v[188:191], v242 offset:7168
	global_load_lds_dwordx4 v[192:193], off
	v_lshl_add_u64 v[192:193], s[4:5], 0, v[220:221]
	s_add_i32 m0, s29, 0xe000
	s_nop 0
	global_load_lds_dwordx4 v[192:193], off
	s_waitcnt vmcnt(8)
	s_waitcnt lgkmcnt(0)
	s_barrier
	s_setprio 1
	s_waitcnt lgkmcnt(0)
	v_mfma_f32_16x16x32_bf16 v[124:127], v[128:131], v[160:163], v[124:127]
	v_mfma_f32_16x16x32_bf16 v[120:123], v[136:139], v[160:163], v[120:123]
	v_mfma_f32_16x16x32_bf16 v[116:119], v[128:131], v[168:171], v[116:119]
	v_mfma_f32_16x16x32_bf16 v[112:115], v[136:139], v[168:171], v[112:115]
	v_mfma_f32_16x16x32_bf16 v[108:111], v[128:131], v[176:179], v[108:111]
	v_mfma_f32_16x16x32_bf16 v[100:103], v[136:139], v[176:179], v[100:103]
	v_mfma_f32_16x16x32_bf16 v[80:83], v[128:131], v[184:187], v[80:83]
	v_mfma_f32_16x16x32_bf16 v[72:75], v[136:139], v[184:187], v[72:75]
	v_mfma_f32_16x16x32_bf16 v[124:127], v[132:135], v[164:167], v[124:127]
	v_mfma_f32_16x16x32_bf16 v[120:123], v[140:143], v[164:167], v[120:123]
	v_mfma_f32_16x16x32_bf16 v[116:119], v[132:135], v[172:175], v[116:119]
	v_mfma_f32_16x16x32_bf16 v[112:115], v[140:143], v[172:175], v[112:115]
	v_mfma_f32_16x16x32_bf16 v[108:111], v[132:135], v[180:183], v[108:111]
	v_mfma_f32_16x16x32_bf16 v[100:103], v[140:143], v[180:183], v[100:103]
	v_mfma_f32_16x16x32_bf16 v[80:83], v[132:135], v[188:191], v[80:83]
	v_mfma_f32_16x16x32_bf16 v[72:75], v[140:143], v[188:191], v[72:75]
	v_mfma_f32_16x16x32_bf16 v[104:107], v[144:147], v[160:163], v[104:107]
	v_mfma_f32_16x16x32_bf16 v[96:99], v[152:155], v[160:163], v[96:99]
	v_mfma_f32_16x16x32_bf16 v[92:95], v[144:147], v[168:171], v[92:95]
	v_mfma_f32_16x16x32_bf16 v[88:91], v[152:155], v[168:171], v[88:91]
	v_mfma_f32_16x16x32_bf16 v[84:87], v[144:147], v[176:179], v[84:87]
	v_mfma_f32_16x16x32_bf16 v[76:79], v[152:155], v[176:179], v[76:79]
	v_mfma_f32_16x16x32_bf16 v[68:71], v[144:147], v[184:187], v[68:71]
	v_mfma_f32_16x16x32_bf16 v[64:67], v[152:155], v[184:187], v[64:67]
	v_mfma_f32_16x16x32_bf16 v[104:107], v[148:151], v[164:167], v[104:107]
	v_mfma_f32_16x16x32_bf16 v[96:99], v[156:159], v[164:167], v[96:99]
	v_mfma_f32_16x16x32_bf16 v[92:95], v[148:151], v[172:175], v[92:95]
	v_mfma_f32_16x16x32_bf16 v[88:91], v[156:159], v[172:175], v[88:91]
	v_mfma_f32_16x16x32_bf16 v[84:87], v[148:151], v[180:183], v[84:87]
	v_mfma_f32_16x16x32_bf16 v[76:79], v[156:159], v[180:183], v[76:79]
	v_mfma_f32_16x16x32_bf16 v[68:71], v[148:151], v[188:191], v[68:71]
	v_mfma_f32_16x16x32_bf16 v[64:67], v[156:159], v[188:191], v[64:67]
	s_setprio 0
	s_barrier
	s_add_i32 s47, s40, s28
	v_lshl_add_u64 v[192:193], s[20:21], 0, v[212:213]
	s_mov_b32 m0, s47
	ds_read_b128 v[160:163], v242 offset:16384
	ds_read_b128 v[164:167], v242 offset:17408
	ds_read_b128 v[168:171], v242 offset:18432
	ds_read_b128 v[172:175], v242 offset:19456
	ds_read_b128 v[176:179], v242 offset:20480
	ds_read_b128 v[180:183], v242 offset:21504
	ds_read_b128 v[184:187], v242 offset:22528
	ds_read_b128 v[188:191], v242 offset:23552
	global_load_lds_dwordx4 v[192:193], off
	s_add_i32 m0, s47, 0x2000
	s_add_u32 s48, s20, 0xb0000
	v_lshl_add_u64 v[194:195], s[20:21], 0, v[216:217]
	s_addc_u32 s49, s21, 0
	s_add_i32 s47, s41, s28
	global_load_lds_dwordx4 v[194:195], off
	v_lshl_add_u64 v[196:197], s[48:49], 0, v[212:213]
	s_mov_b32 m0, s47
	v_lshl_add_u64 v[198:199], s[22:23], 0, v[214:215]
	global_load_lds_dwordx4 v[196:197], off
	v_lshl_add_u64 v[196:197], s[48:49], 0, v[216:217]
	s_add_i32 m0, s47, 0x2000
	s_nop 0
	global_load_lds_dwordx4 v[196:197], off
	v_lshl_add_u64 v[196:197], s[22:23], 0, v[210:211]
	s_mov_b32 m0, s29
	s_nop 0
	global_load_lds_dwordx4 v[196:197], off
	s_mov_b32 m0, s30
	s_nop 0
	global_load_lds_dwordx4 v[198:199], off
	s_waitcnt vmcnt(8)
	s_waitcnt lgkmcnt(0)
	s_barrier
	s_setprio 1
	s_waitcnt lgkmcnt(0)
	v_mfma_f32_16x16x32_bf16 v[60:63], v[128:131], v[160:163], v[60:63]
	v_mfma_f32_16x16x32_bf16 v[56:59], v[136:139], v[160:163], v[56:59]
	v_mfma_f32_16x16x32_bf16 v[52:55], v[128:131], v[168:171], v[52:55]
	v_mfma_f32_16x16x32_bf16 v[48:51], v[136:139], v[168:171], v[48:51]
	v_mfma_f32_16x16x32_bf16 v[44:47], v[128:131], v[176:179], v[44:47]
	v_mfma_f32_16x16x32_bf16 v[36:39], v[136:139], v[176:179], v[36:39]
	v_mfma_f32_16x16x32_bf16 v[20:23], v[128:131], v[184:187], v[20:23]
	v_mfma_f32_16x16x32_bf16 v[12:15], v[136:139], v[184:187], v[12:15]
	v_mfma_f32_16x16x32_bf16 v[60:63], v[132:135], v[164:167], v[60:63]
	v_mfma_f32_16x16x32_bf16 v[56:59], v[140:143], v[164:167], v[56:59]
	v_mfma_f32_16x16x32_bf16 v[52:55], v[132:135], v[172:175], v[52:55]
	v_mfma_f32_16x16x32_bf16 v[48:51], v[140:143], v[172:175], v[48:51]
	v_mfma_f32_16x16x32_bf16 v[44:47], v[132:135], v[180:183], v[44:47]
	v_mfma_f32_16x16x32_bf16 v[36:39], v[140:143], v[180:183], v[36:39]
	v_mfma_f32_16x16x32_bf16 v[20:23], v[132:135], v[188:191], v[20:23]
	v_mfma_f32_16x16x32_bf16 v[12:15], v[140:143], v[188:191], v[12:15]
	v_mfma_f32_16x16x32_bf16 v[40:43], v[144:147], v[160:163], v[40:43]
	v_mfma_f32_16x16x32_bf16 v[32:35], v[152:155], v[160:163], v[32:35]
	v_mfma_f32_16x16x32_bf16 v[28:31], v[144:147], v[168:171], v[28:31]
	v_mfma_f32_16x16x32_bf16 v[24:27], v[152:155], v[168:171], v[24:27]
	v_mfma_f32_16x16x32_bf16 v[16:19], v[144:147], v[176:179], v[16:19]
	v_mfma_f32_16x16x32_bf16 v[8:11], v[152:155], v[176:179], v[8:11]
	v_mfma_f32_16x16x32_bf16 v[4:7], v[144:147], v[184:187], v[4:7]
	v_mfma_f32_16x16x32_bf16 v[0:3], v[152:155], v[184:187], v[0:3]
	v_mfma_f32_16x16x32_bf16 v[40:43], v[148:151], v[164:167], v[40:43]
	v_mfma_f32_16x16x32_bf16 v[32:35], v[156:159], v[164:167], v[32:35]
	v_mfma_f32_16x16x32_bf16 v[28:31], v[148:151], v[172:175], v[28:31]
	v_mfma_f32_16x16x32_bf16 v[24:27], v[156:159], v[172:175], v[24:27]
	v_mfma_f32_16x16x32_bf16 v[16:19], v[148:151], v[180:183], v[16:19]
	v_mfma_f32_16x16x32_bf16 v[8:11], v[156:159], v[180:183], v[8:11]
	v_mfma_f32_16x16x32_bf16 v[4:7], v[148:151], v[188:191], v[4:7]
	v_mfma_f32_16x16x32_bf16 v[0:3], v[156:159], v[188:191], v[0:3]
	s_setprio 0
	s_barrier
	s_add_i32 s47, 0, 0x18000
	s_add_i32 s48, 0, 0x1c000
	v_add_u32_e32 v140, s47, v238
	v_add_u32_e32 v156, s48, v238
	ds_read_b128 v[128:131], v140
	ds_read_b128 v[132:135], v140 offset:1024
	ds_read_b128 v[136:139], v140 offset:2048
	ds_read_b128 v[140:143], v140 offset:3072
	ds_read_b128 v[144:147], v156
	ds_read_b128 v[148:151], v156 offset:1024
	ds_read_b128 v[152:155], v156 offset:2048
	ds_read_b128 v[156:159], v156 offset:3072
	s_add_u32 s22, s22, 0xb0000
	s_addc_u32 s23, s23, 0
	s_mov_b32 m0, s31
	v_lshl_add_u64 v[200:201], s[22:23], 0, v[210:211]
	ds_read_b128 v[160:163], v242 offset:32768
	ds_read_b128 v[164:167], v242 offset:33792
	ds_read_b128 v[168:171], v242 offset:34816
	ds_read_b128 v[172:175], v242 offset:35840
	ds_read_b128 v[176:179], v242 offset:36864
	ds_read_b128 v[180:183], v242 offset:37888
	ds_read_b128 v[184:187], v242 offset:38912
	ds_read_b128 v[188:191], v242 offset:39936
	global_load_lds_dwordx4 v[200:201], off
	v_lshl_add_u64 v[200:201], s[22:23], 0, v[214:215]
	s_mov_b32 m0, s33
	s_nop 0
	global_load_lds_dwordx4 v[200:201], off
	s_waitcnt vmcnt(8)
	s_waitcnt lgkmcnt(0)
	s_barrier
	s_setprio 1
	s_waitcnt lgkmcnt(0)
	v_mfma_f32_16x16x32_bf16 v[124:127], v[128:131], v[160:163], v[124:127]
	v_mfma_f32_16x16x32_bf16 v[120:123], v[136:139], v[160:163], v[120:123]
	v_mfma_f32_16x16x32_bf16 v[116:119], v[128:131], v[168:171], v[116:119]
	v_mfma_f32_16x16x32_bf16 v[112:115], v[136:139], v[168:171], v[112:115]
	v_mfma_f32_16x16x32_bf16 v[108:111], v[128:131], v[176:179], v[108:111]
	v_mfma_f32_16x16x32_bf16 v[100:103], v[136:139], v[176:179], v[100:103]
	v_mfma_f32_16x16x32_bf16 v[80:83], v[128:131], v[184:187], v[80:83]
	v_mfma_f32_16x16x32_bf16 v[72:75], v[136:139], v[184:187], v[72:75]
	v_mfma_f32_16x16x32_bf16 v[124:127], v[132:135], v[164:167], v[124:127]
	v_mfma_f32_16x16x32_bf16 v[120:123], v[140:143], v[164:167], v[120:123]
	v_mfma_f32_16x16x32_bf16 v[116:119], v[132:135], v[172:175], v[116:119]
	v_mfma_f32_16x16x32_bf16 v[112:115], v[140:143], v[172:175], v[112:115]
	v_mfma_f32_16x16x32_bf16 v[108:111], v[132:135], v[180:183], v[108:111]
	v_mfma_f32_16x16x32_bf16 v[100:103], v[140:143], v[180:183], v[100:103]
	v_mfma_f32_16x16x32_bf16 v[80:83], v[132:135], v[188:191], v[80:83]
	v_mfma_f32_16x16x32_bf16 v[72:75], v[140:143], v[188:191], v[72:75]
	v_mfma_f32_16x16x32_bf16 v[104:107], v[144:147], v[160:163], v[104:107]
	v_mfma_f32_16x16x32_bf16 v[96:99], v[152:155], v[160:163], v[96:99]
	v_mfma_f32_16x16x32_bf16 v[92:95], v[144:147], v[168:171], v[92:95]
	v_mfma_f32_16x16x32_bf16 v[88:91], v[152:155], v[168:171], v[88:91]
	v_mfma_f32_16x16x32_bf16 v[84:87], v[144:147], v[176:179], v[84:87]
	v_mfma_f32_16x16x32_bf16 v[76:79], v[152:155], v[176:179], v[76:79]
	v_mfma_f32_16x16x32_bf16 v[68:71], v[144:147], v[184:187], v[68:71]
	v_mfma_f32_16x16x32_bf16 v[64:67], v[152:155], v[184:187], v[64:67]
	v_mfma_f32_16x16x32_bf16 v[104:107], v[148:151], v[164:167], v[104:107]
	v_mfma_f32_16x16x32_bf16 v[96:99], v[156:159], v[164:167], v[96:99]
	v_mfma_f32_16x16x32_bf16 v[92:95], v[148:151], v[172:175], v[92:95]
	v_mfma_f32_16x16x32_bf16 v[88:91], v[156:159], v[172:175], v[88:91]
	v_mfma_f32_16x16x32_bf16 v[84:87], v[148:151], v[180:183], v[84:87]
	v_mfma_f32_16x16x32_bf16 v[76:79], v[156:159], v[180:183], v[76:79]
	v_mfma_f32_16x16x32_bf16 v[68:71], v[148:151], v[188:191], v[68:71]
	v_mfma_f32_16x16x32_bf16 v[64:67], v[156:159], v[188:191], v[64:67]
	s_setprio 0
	s_barrier
	s_add_i32 s22, s47, s28
	v_lshl_add_u64 v[192:193], v[192:193], 0, s[16:17]
	s_mov_b32 m0, s22
	ds_read_b128 v[160:163], v242 offset:49152
	ds_read_b128 v[164:167], v242 offset:50176
	ds_read_b128 v[168:171], v242 offset:51200
	ds_read_b128 v[172:175], v242 offset:52224
	ds_read_b128 v[176:179], v242 offset:53248
	ds_read_b128 v[180:183], v242 offset:54272
	ds_read_b128 v[184:187], v242 offset:55296
	ds_read_b128 v[188:191], v242 offset:56320
	global_load_lds_dwordx4 v[192:193], off
	s_add_i32 m0, s22, 0x2000
	s_add_u32 s20, s20, 0xb0080
	v_lshl_add_u64 v[192:193], v[194:195], 0, s[16:17]
	s_addc_u32 s21, s21, 0
	s_add_i32 s22, s48, s28
	global_load_lds_dwordx4 v[192:193], off
	v_lshl_add_u64 v[192:193], s[20:21], 0, v[212:213]
	s_mov_b32 m0, s22
	s_nop 0
	global_load_lds_dwordx4 v[192:193], off
	v_lshl_add_u64 v[192:193], s[20:21], 0, v[216:217]
	s_add_i32 m0, s22, 0x2000
	s_nop 0
	global_load_lds_dwordx4 v[192:193], off
	v_lshl_add_u64 v[192:193], v[196:197], 0, s[16:17]
	s_mov_b32 m0, s35
	s_nop 0
	global_load_lds_dwordx4 v[192:193], off
	v_lshl_add_u64 v[192:193], v[198:199], 0, s[16:17]
	s_mov_b32 m0, s36
	s_nop 0
	global_load_lds_dwordx4 v[192:193], off
	s_waitcnt vmcnt(8)
	s_waitcnt lgkmcnt(0)
	s_barrier
	s_setprio 1
	s_waitcnt lgkmcnt(0)
	v_mfma_f32_16x16x32_bf16 v[60:63], v[128:131], v[160:163], v[60:63]
	v_mfma_f32_16x16x32_bf16 v[56:59], v[136:139], v[160:163], v[56:59]
	v_mfma_f32_16x16x32_bf16 v[52:55], v[128:131], v[168:171], v[52:55]
	v_mfma_f32_16x16x32_bf16 v[48:51], v[136:139], v[168:171], v[48:51]
	v_mfma_f32_16x16x32_bf16 v[44:47], v[128:131], v[176:179], v[44:47]
	v_mfma_f32_16x16x32_bf16 v[36:39], v[136:139], v[176:179], v[36:39]
	v_mfma_f32_16x16x32_bf16 v[20:23], v[128:131], v[184:187], v[20:23]
	v_mfma_f32_16x16x32_bf16 v[12:15], v[136:139], v[184:187], v[12:15]
	v_mfma_f32_16x16x32_bf16 v[60:63], v[132:135], v[164:167], v[60:63]
	v_mfma_f32_16x16x32_bf16 v[56:59], v[140:143], v[164:167], v[56:59]
	v_mfma_f32_16x16x32_bf16 v[52:55], v[132:135], v[172:175], v[52:55]
	v_mfma_f32_16x16x32_bf16 v[48:51], v[140:143], v[172:175], v[48:51]
	v_mfma_f32_16x16x32_bf16 v[44:47], v[132:135], v[180:183], v[44:47]
	v_mfma_f32_16x16x32_bf16 v[36:39], v[140:143], v[180:183], v[36:39]
	v_mfma_f32_16x16x32_bf16 v[20:23], v[132:135], v[188:191], v[20:23]
	v_mfma_f32_16x16x32_bf16 v[12:15], v[140:143], v[188:191], v[12:15]
	v_mfma_f32_16x16x32_bf16 v[40:43], v[144:147], v[160:163], v[40:43]
	v_mfma_f32_16x16x32_bf16 v[32:35], v[152:155], v[160:163], v[32:35]
	v_mfma_f32_16x16x32_bf16 v[28:31], v[144:147], v[168:171], v[28:31]
	v_mfma_f32_16x16x32_bf16 v[24:27], v[152:155], v[168:171], v[24:27]
	v_mfma_f32_16x16x32_bf16 v[16:19], v[144:147], v[176:179], v[16:19]
	v_mfma_f32_16x16x32_bf16 v[8:11], v[152:155], v[176:179], v[8:11]
	v_mfma_f32_16x16x32_bf16 v[4:7], v[144:147], v[184:187], v[4:7]
	v_mfma_f32_16x16x32_bf16 v[0:3], v[152:155], v[184:187], v[0:3]
	v_mfma_f32_16x16x32_bf16 v[40:43], v[148:151], v[164:167], v[40:43]
	v_mfma_f32_16x16x32_bf16 v[32:35], v[156:159], v[164:167], v[32:35]
	v_mfma_f32_16x16x32_bf16 v[28:31], v[148:151], v[172:175], v[28:31]
	v_mfma_f32_16x16x32_bf16 v[24:27], v[156:159], v[172:175], v[24:27]
	v_mfma_f32_16x16x32_bf16 v[16:19], v[148:151], v[180:183], v[16:19]
	v_mfma_f32_16x16x32_bf16 v[8:11], v[156:159], v[180:183], v[8:11]
	v_mfma_f32_16x16x32_bf16 v[4:7], v[148:151], v[188:191], v[4:7]
	v_mfma_f32_16x16x32_bf16 v[0:3], v[156:159], v[188:191], v[0:3]
	s_setprio 0
	s_barrier
	s_add_i32 s46, s46, 2
	s_add_u32 s4, s4, 0x100
	s_addc_u32 s5, s5, 0
	s_add_u32 s44, s44, 0x100
	s_addc_u32 s45, s45, 0
	s_cmp_gt_u32 s46, 41
	s_cbranch_scc0 .LBB0_1318
	s_cmp_gt_i32 s24, 63
	s_cselect_b64 s[20:21], -1, 0
	s_lshl_b32 s4, s24, 2
	s_add_i32 s45, s37, s4
	s_ashr_i32 s44, s24, 3
	s_cmp_lt_i32 s24, 64
	s_cselect_b64 s[4:5], -1, 0
	s_and_b64 vcc, s[4:5], exec
	s_cselect_b32 s22, s44, s45
	v_lshl_or_b32 v128, s25, 8, v239
	v_lshl_add_u32 v228, s24, 8, v237
	s_mul_i32 s24, s22, 0x9000
	v_ashrrev_i32_e32 v129, 31, v128
	v_add_u32_e32 v130, 0xffffc000, v228
	s_mul_hi_i32 s25, s22, 0x9000
	s_cselect_b32 s23, s73, s9
	s_cselect_b32 s22, s72, s8
	s_add_u32 s24, s12, s24
	v_or_b32_e32 v230, 16, v228
	v_add_u32_e32 v140, 0xffffc010, v228
	v_or_b32_e32 v232, 32, v228
	v_add_u32_e32 v156, 0xffffc020, v228
	v_cndmask_b32_e64 v130, v130, v228, s[4:5]
	s_addc_u32 s25, s13, s25
	v_lshlrev_b64 v[226:227], 2, v[128:129]
	v_cndmask_b32_e64 v140, v140, v230, s[4:5]
	v_cndmask_b32_e64 v156, v156, v232, s[4:5]
	v_lshl_add_u64 v[128:129], s[24:25], 0, v[226:227]
	v_ashrrev_i32_e32 v131, 31, v130
	v_ashrrev_i32_e32 v141, 31, v140
	v_ashrrev_i32_e32 v157, 31, v156
	global_load_dwordx4 v[196:199], v[128:129], off offset:16
	global_load_dwordx4 v[204:207], v[128:129], off
	global_load_dwordx4 v[192:195], v[128:129], off offset:528
	global_load_dwordx4 v[200:203], v[128:129], off offset:512
	v_lshlrev_b64 v[128:129], 12, v[130:131]
	v_lshlrev_b64 v[140:141], 12, v[140:141]
	v_lshlrev_b64 v[156:157], 12, v[156:157]
	v_lshl_add_u64 v[128:129], s[22:23], 0, v[128:129]
	v_lshl_add_u64 v[140:141], s[22:23], 0, v[140:141]
	v_lshl_add_u64 v[156:157], s[22:23], 0, v[156:157]
	v_lshl_add_u64 v[136:137], v[128:129], 0, v[226:227]
	v_lshl_add_u64 v[152:153], v[140:141], 0, v[226:227]
	v_lshl_add_u64 v[168:169], v[156:157], 0, v[226:227]
	global_load_dwordx4 v[132:135], v[136:137], off offset:16
	global_load_dwordx4 v[144:147], v[136:137], off
	global_load_dwordx4 v[128:131], v[136:137], off offset:528
	s_nop 0
	global_load_dwordx4 v[136:139], v[136:137], off offset:512
	s_nop 0
	global_load_dwordx4 v[148:151], v[152:153], off offset:16
	global_load_dwordx4 v[160:163], v[152:153], off
	global_load_dwordx4 v[140:143], v[152:153], off offset:528
	s_nop 0
	global_load_dwordx4 v[152:155], v[152:153], off offset:512
	s_nop 0
	global_load_dwordx4 v[164:167], v[168:169], off offset:16
	global_load_dwordx4 v[172:175], v[168:169], off
	global_load_dwordx4 v[156:159], v[168:169], off offset:528
	s_nop 0
	global_load_dwordx4 v[168:171], v[168:169], off offset:512
	v_or_b32_e32 v178, 48, v228
	s_mov_b64 s[24:25], -1
	v_ashrrev_i32_e32 v179, 31, v178
	s_cbranch_vccnz .LBB0_1321
	v_add_u32_e32 v176, 0xffffc030, v228
	v_ashrrev_i32_e32 v177, 31, v176
	v_lshlrev_b64 v[176:177], 12, v[176:177]
	v_lshl_add_u64 v[176:177], s[8:9], 0, v[176:177]
	v_lshlrev_b64 v[234:235], 12, v[178:179]
	s_mov_b64 s[24:25], 0
